# merge tile: the projection GEMM's first two LDS-DMA tiles are issued right after the gate GEMM's closing barrier (land during the sigmoid section)
# speedup vs baseline: 1.0017x; 1.0017x over previous
.Lgp_ma:
	s_add_u32 m0, s14, 0x800
	s_nop 0
	global_load_lds_dwordx4 v[148:149], off
	s_add_u32 m0, s14, 0x1800
	s_nop 0
	global_load_lds_dwordx4 v[152:153], off
	s_add_u32 m0, s14, 0x2800
	s_nop 0
	global_load_lds_dwordx4 v[156:157], off
	s_add_u32 m0, s14, 0x3800
	s_nop 0
	global_load_lds_dwordx4 v[160:161], off
	s_add_u32 m0, s14, 0x4800
	s_nop 0
	global_load_lds_dwordx4 v[150:151], off
	s_add_u32 m0, s14, 0x5800
	s_nop 0
	global_load_lds_dwordx4 v[154:155], off
	s_add_u32 m0, s14, 0x6800
	s_nop 0
	global_load_lds_dwordx4 v[158:159], off
	s_add_u32 m0, s14, 0x7800
	s_nop 0
	global_load_lds_dwordx4 v[162:163], off
	s_add_u32 m0, s14, 0x8780
	s_nop 0
	global_load_lds_dwordx4 v[148:149], off offset:128
	s_add_u32 m0, s14, 0x9780
	s_nop 0
	global_load_lds_dwordx4 v[152:153], off offset:128
	s_add_u32 m0, s14, 0xa780
	s_nop 0
	global_load_lds_dwordx4 v[156:157], off offset:128
	s_add_u32 m0, s14, 0xb780
	s_nop 0
	global_load_lds_dwordx4 v[160:161], off offset:128
	s_add_u32 m0, s14, 0xc780
	s_nop 0
	global_load_lds_dwordx4 v[150:151], off offset:128
	s_add_u32 m0, s14, 0xd780
	s_nop 0
	global_load_lds_dwordx4 v[154:155], off offset:128
	s_add_u32 m0, s14, 0xe780
	s_nop 0
	global_load_lds_dwordx4 v[158:159], off offset:128
	s_add_u32 m0, s14, 0xf780
	s_nop 0
	global_load_lds_dwordx4 v[162:163], off offset:128
	s_waitcnt vmcnt(8)
	s_barrier
	ds_read_b128 v[66:69], v130 offset:2048
	ds_read_b128 v[70:73], v130 offset:6144
	ds_read_b128 v[74:77], v134 offset:2048
	ds_read_b128 v[78:81], v134 offset:6144
	ds_read_b128 v[82:85], v131 offset:2048
	ds_read_b128 v[86:89], v131 offset:6144
	ds_read_b128 v[90:93], v135 offset:2048
	ds_read_b128 v[94:97], v135 offset:6144
	ds_read_b128 v[98:101], v132 offset:2048
	ds_read_b128 v[102:105], v132 offset:6144
	ds_read_b128 v[106:109], v136 offset:2048
	ds_read_b128 v[110:113], v136 offset:6144
	ds_read_b128 v[114:117], v133 offset:2048
	ds_read_b128 v[118:121], v133 offset:6144
	ds_read_b128 v[122:125], v137 offset:2048
	ds_read_b128 v[126:129], v137 offset:6144
	s_waitcnt lgkmcnt(0)
	s_barrier
	s_add_u32 m0, s14, 0x700
	s_nop 0
	global_load_lds_dwordx4 v[148:149], off offset:256
	s_add_u32 m0, s14, 0x1700
	s_nop 0
	global_load_lds_dwordx4 v[152:153], off offset:256
	s_add_u32 m0, s14, 0x2700
	s_nop 0
	global_load_lds_dwordx4 v[156:157], off offset:256
	s_add_u32 m0, s14, 0x3700
	s_nop 0
	global_load_lds_dwordx4 v[160:161], off offset:256
	s_add_u32 m0, s14, 0x4700
	s_nop 0
	global_load_lds_dwordx4 v[150:151], off offset:256
	s_add_u32 m0, s14, 0x5700
	s_nop 0
	global_load_lds_dwordx4 v[154:155], off offset:256
	s_add_u32 m0, s14, 0x6700
	s_nop 0
	global_load_lds_dwordx4 v[158:159], off offset:256
	s_add_u32 m0, s14, 0x7700
	s_nop 0
	global_load_lds_dwordx4 v[162:163], off offset:256
	v_mfma_f32_32x32x16_bf16 v[50:65], v[66:69], v[74:77], 0
	v_mfma_f32_32x32x16_bf16 v[34:49], v[66:69], v[78:81], 0
	v_mfma_f32_32x32x16_bf16 v[18:33], v[70:73], v[74:77], 0
	v_mfma_f32_32x32x16_bf16 v[2:17], v[70:73], v[78:81], 0
	s_waitcnt vmcnt(8)
	s_barrier
	ds_read_b128 v[66:69], v130 offset:34816
	ds_read_b128 v[70:73], v130 offset:38912
	ds_read_b128 v[74:77], v134 offset:34816
	ds_read_b128 v[78:81], v134 offset:38912
	v_mfma_f32_32x32x16_bf16 v[50:65], v[82:85], v[90:93], v[50:65]
	v_mfma_f32_32x32x16_bf16 v[34:49], v[82:85], v[94:97], v[34:49]
	v_mfma_f32_32x32x16_bf16 v[18:33], v[86:89], v[90:93], v[18:33]
	v_mfma_f32_32x32x16_bf16 v[2:17], v[86:89], v[94:97], v[2:17]
	ds_read_b128 v[82:85], v131 offset:34816
	ds_read_b128 v[86:89], v131 offset:38912
	ds_read_b128 v[90:93], v135 offset:34816
	ds_read_b128 v[94:97], v135 offset:38912
	v_mfma_f32_32x32x16_bf16 v[50:65], v[98:101], v[106:109], v[50:65]
	v_mfma_f32_32x32x16_bf16 v[34:49], v[98:101], v[110:113], v[34:49]
	v_mfma_f32_32x32x16_bf16 v[18:33], v[102:105], v[106:109], v[18:33]
	v_mfma_f32_32x32x16_bf16 v[2:17], v[102:105], v[110:113], v[2:17]
	ds_read_b128 v[98:101], v132 offset:34816
	ds_read_b128 v[102:105], v132 offset:38912
	ds_read_b128 v[106:109], v136 offset:34816
	ds_read_b128 v[110:113], v136 offset:38912
	v_mfma_f32_32x32x16_bf16 v[50:65], v[114:117], v[122:125], v[50:65]
	v_mfma_f32_32x32x16_bf16 v[34:49], v[114:117], v[126:129], v[34:49]
	v_mfma_f32_32x32x16_bf16 v[18:33], v[118:121], v[122:125], v[18:33]
	v_mfma_f32_32x32x16_bf16 v[2:17], v[118:121], v[126:129], v[2:17]
	ds_read_b128 v[114:117], v133 offset:34816
	ds_read_b128 v[118:121], v133 offset:38912
	ds_read_b128 v[122:125], v137 offset:34816
	ds_read_b128 v[126:129], v137 offset:38912
	s_waitcnt lgkmcnt(0)
	s_barrier
	v_mfma_f32_32x32x16_bf16 v[50:65], v[66:69], v[74:77], v[50:65]
	s_add_u32 m0, s14, 0x8680
	s_nop 0
	global_load_lds_dwordx4 v[148:149], off offset:384
	s_add_u32 m0, s14, 0x9680
	s_nop 0
	global_load_lds_dwordx4 v[152:153], off offset:384
	v_mfma_f32_32x32x16_bf16 v[34:49], v[66:69], v[78:81], v[34:49]
	s_add_u32 m0, s14, 0xa680
	s_nop 0
	global_load_lds_dwordx4 v[156:157], off offset:384
	s_add_u32 m0, s14, 0xb680
	s_nop 0
	global_load_lds_dwordx4 v[160:161], off offset:384
	v_mfma_f32_32x32x16_bf16 v[18:33], v[70:73], v[74:77], v[18:33]
	s_add_u32 m0, s14, 0xc680
	s_nop 0
	global_load_lds_dwordx4 v[150:151], off offset:384
	s_add_u32 m0, s14, 0xd680
	s_nop 0
	global_load_lds_dwordx4 v[154:155], off offset:384
	v_mfma_f32_32x32x16_bf16 v[2:17], v[70:73], v[78:81], v[2:17]
	s_add_u32 m0, s14, 0xe680
	s_nop 0
	global_load_lds_dwordx4 v[158:159], off offset:384
	s_add_u32 m0, s14, 0xf680
	s_nop 0
	global_load_lds_dwordx4 v[162:163], off offset:384
	s_waitcnt vmcnt(8)
	s_barrier
	ds_read_b128 v[66:69], v130 offset:2048
	ds_read_b128 v[70:73], v130 offset:6144
	ds_read_b128 v[74:77], v134 offset:2048
	ds_read_b128 v[78:81], v134 offset:6144
	v_mfma_f32_32x32x16_bf16 v[50:65], v[82:85], v[90:93], v[50:65]
	v_mfma_f32_32x32x16_bf16 v[34:49], v[82:85], v[94:97], v[34:49]
	v_mfma_f32_32x32x16_bf16 v[18:33], v[86:89], v[90:93], v[18:33]
	v_mfma_f32_32x32x16_bf16 v[2:17], v[86:89], v[94:97], v[2:17]
	ds_read_b128 v[82:85], v131 offset:2048
	ds_read_b128 v[86:89], v131 offset:6144
	ds_read_b128 v[90:93], v135 offset:2048
	ds_read_b128 v[94:97], v135 offset:6144
	v_mfma_f32_32x32x16_bf16 v[50:65], v[98:101], v[106:109], v[50:65]
	v_mfma_f32_32x32x16_bf16 v[34:49], v[98:101], v[110:113], v[34:49]
	v_mfma_f32_32x32x16_bf16 v[18:33], v[102:105], v[106:109], v[18:33]
	v_mfma_f32_32x32x16_bf16 v[2:17], v[102:105], v[110:113], v[2:17]
	ds_read_b128 v[98:101], v132 offset:2048
	ds_read_b128 v[102:105], v132 offset:6144
	ds_read_b128 v[106:109], v136 offset:2048
	ds_read_b128 v[110:113], v136 offset:6144
	v_mfma_f32_32x32x16_bf16 v[50:65], v[114:117], v[122:125], v[50:65]
	v_mfma_f32_32x32x16_bf16 v[34:49], v[114:117], v[126:129], v[34:49]
	v_mfma_f32_32x32x16_bf16 v[18:33], v[118:121], v[122:125], v[18:33]
	v_mfma_f32_32x32x16_bf16 v[2:17], v[118:121], v[126:129], v[2:17]
	ds_read_b128 v[114:117], v133 offset:2048
	ds_read_b128 v[118:121], v133 offset:6144
	ds_read_b128 v[122:125], v137 offset:2048
	ds_read_b128 v[126:129], v137 offset:6144
	s_waitcnt lgkmcnt(0)
	s_barrier
	v_mfma_f32_32x32x16_bf16 v[50:65], v[66:69], v[74:77], v[50:65]
	s_add_u32 m0, s14, 0x600
	s_nop 0
	global_load_lds_dwordx4 v[148:149], off offset:512
	s_add_u32 m0, s14, 0x1600
	s_nop 0
	global_load_lds_dwordx4 v[152:153], off offset:512
	v_mfma_f32_32x32x16_bf16 v[34:49], v[66:69], v[78:81], v[34:49]
	s_add_u32 m0, s14, 0x2600
	s_nop 0
	global_load_lds_dwordx4 v[156:157], off offset:512
	s_add_u32 m0, s14, 0x3600
	s_nop 0
	global_load_lds_dwordx4 v[160:161], off offset:512
	v_mfma_f32_32x32x16_bf16 v[18:33], v[70:73], v[74:77], v[18:33]
	s_add_u32 m0, s14, 0x4600
	s_nop 0
	global_load_lds_dwordx4 v[150:151], off offset:512
	s_add_u32 m0, s14, 0x5600
	s_nop 0
	global_load_lds_dwordx4 v[154:155], off offset:512
	v_mfma_f32_32x32x16_bf16 v[2:17], v[70:73], v[78:81], v[2:17]
	s_add_u32 m0, s14, 0x6600
	s_nop 0
	global_load_lds_dwordx4 v[158:159], off offset:512
	s_add_u32 m0, s14, 0x7600
	s_nop 0
	global_load_lds_dwordx4 v[162:163], off offset:512
	s_waitcnt vmcnt(8)
	s_barrier
	ds_read_b128 v[66:69], v130 offset:34816
	ds_read_b128 v[70:73], v130 offset:38912
	ds_read_b128 v[74:77], v134 offset:34816
	ds_read_b128 v[78:81], v134 offset:38912
	v_mfma_f32_32x32x16_bf16 v[50:65], v[82:85], v[90:93], v[50:65]
	v_mfma_f32_32x32x16_bf16 v[34:49], v[82:85], v[94:97], v[34:49]
	v_mfma_f32_32x32x16_bf16 v[18:33], v[86:89], v[90:93], v[18:33]
	v_mfma_f32_32x32x16_bf16 v[2:17], v[86:89], v[94:97], v[2:17]
	ds_read_b128 v[82:85], v131 offset:34816
	ds_read_b128 v[86:89], v131 offset:38912
	ds_read_b128 v[90:93], v135 offset:34816
	ds_read_b128 v[94:97], v135 offset:38912
	v_mfma_f32_32x32x16_bf16 v[50:65], v[98:101], v[106:109], v[50:65]
	v_mfma_f32_32x32x16_bf16 v[34:49], v[98:101], v[110:113], v[34:49]
	v_mfma_f32_32x32x16_bf16 v[18:33], v[102:105], v[106:109], v[18:33]
	v_mfma_f32_32x32x16_bf16 v[2:17], v[102:105], v[110:113], v[2:17]
	ds_read_b128 v[98:101], v132 offset:34816
	ds_read_b128 v[102:105], v132 offset:38912
	ds_read_b128 v[106:109], v136 offset:34816
	ds_read_b128 v[110:113], v136 offset:38912
	v_mfma_f32_32x32x16_bf16 v[50:65], v[114:117], v[122:125], v[50:65]
	v_mfma_f32_32x32x16_bf16 v[34:49], v[114:117], v[126:129], v[34:49]
	v_mfma_f32_32x32x16_bf16 v[18:33], v[118:121], v[122:125], v[18:33]
	v_mfma_f32_32x32x16_bf16 v[2:17], v[118:121], v[126:129], v[2:17]
	ds_read_b128 v[114:117], v133 offset:34816
	ds_read_b128 v[118:121], v133 offset:38912
	ds_read_b128 v[122:125], v137 offset:34816
	ds_read_b128 v[126:129], v137 offset:38912
	s_waitcnt lgkmcnt(0)
	s_barrier
	v_mfma_f32_32x32x16_bf16 v[50:65], v[66:69], v[74:77], v[50:65]
	s_add_u32 m0, s14, 0x8580
	s_nop 0
	global_load_lds_dwordx4 v[148:149], off offset:640
	s_add_u32 m0, s14, 0x9580
	s_nop 0
	global_load_lds_dwordx4 v[152:153], off offset:640
	v_mfma_f32_32x32x16_bf16 v[34:49], v[66:69], v[78:81], v[34:49]
	s_add_u32 m0, s14, 0xa580
	s_nop 0
	global_load_lds_dwordx4 v[156:157], off offset:640
	s_add_u32 m0, s14, 0xb580
	s_nop 0
	global_load_lds_dwordx4 v[160:161], off offset:640
	v_mfma_f32_32x32x16_bf16 v[18:33], v[70:73], v[74:77], v[18:33]
	s_add_u32 m0, s14, 0xc580
	s_nop 0
	global_load_lds_dwordx4 v[150:151], off offset:640
	s_add_u32 m0, s14, 0xd580
	s_nop 0
	global_load_lds_dwordx4 v[154:155], off offset:640
	v_mfma_f32_32x32x16_bf16 v[2:17], v[70:73], v[78:81], v[2:17]
	s_add_u32 m0, s14, 0xe580
	s_nop 0
	global_load_lds_dwordx4 v[158:159], off offset:640
	s_add_u32 m0, s14, 0xf580
	s_nop 0
	global_load_lds_dwordx4 v[162:163], off offset:640
	s_waitcnt vmcnt(8)
	s_barrier
	ds_read_b128 v[66:69], v130 offset:2048
	ds_read_b128 v[70:73], v130 offset:6144
	ds_read_b128 v[74:77], v134 offset:2048
	ds_read_b128 v[78:81], v134 offset:6144
	v_mfma_f32_32x32x16_bf16 v[50:65], v[82:85], v[90:93], v[50:65]
	v_mfma_f32_32x32x16_bf16 v[34:49], v[82:85], v[94:97], v[34:49]
	v_mfma_f32_32x32x16_bf16 v[18:33], v[86:89], v[90:93], v[18:33]
	v_mfma_f32_32x32x16_bf16 v[2:17], v[86:89], v[94:97], v[2:17]
	ds_read_b128 v[82:85], v131 offset:2048
	ds_read_b128 v[86:89], v131 offset:6144
	ds_read_b128 v[90:93], v135 offset:2048
	ds_read_b128 v[94:97], v135 offset:6144
	v_mfma_f32_32x32x16_bf16 v[50:65], v[98:101], v[106:109], v[50:65]
	v_mfma_f32_32x32x16_bf16 v[34:49], v[98:101], v[110:113], v[34:49]
	v_mfma_f32_32x32x16_bf16 v[18:33], v[102:105], v[106:109], v[18:33]
	v_mfma_f32_32x32x16_bf16 v[2:17], v[102:105], v[110:113], v[2:17]
	ds_read_b128 v[98:101], v132 offset:2048
	ds_read_b128 v[102:105], v132 offset:6144
	ds_read_b128 v[106:109], v136 offset:2048
	ds_read_b128 v[110:113], v136 offset:6144
	v_mfma_f32_32x32x16_bf16 v[50:65], v[114:117], v[122:125], v[50:65]
	v_mfma_f32_32x32x16_bf16 v[34:49], v[114:117], v[126:129], v[34:49]
	v_mfma_f32_32x32x16_bf16 v[18:33], v[118:121], v[122:125], v[18:33]
	v_mfma_f32_32x32x16_bf16 v[2:17], v[118:121], v[126:129], v[2:17]
	ds_read_b128 v[114:117], v133 offset:2048
	ds_read_b128 v[118:121], v133 offset:6144
	ds_read_b128 v[122:125], v137 offset:2048
	ds_read_b128 v[126:129], v137 offset:6144
	s_waitcnt lgkmcnt(0)
	s_barrier
	v_mfma_f32_32x32x16_bf16 v[50:65], v[66:69], v[74:77], v[50:65]
	s_add_u32 m0, s14, 0x500
	s_nop 0
	global_load_lds_dwordx4 v[148:149], off offset:768
	s_add_u32 m0, s14, 0x1500
	s_nop 0
	global_load_lds_dwordx4 v[152:153], off offset:768
	v_mfma_f32_32x32x16_bf16 v[34:49], v[66:69], v[78:81], v[34:49]
	s_add_u32 m0, s14, 0x2500
	s_nop 0
	global_load_lds_dwordx4 v[156:157], off offset:768
	s_add_u32 m0, s14, 0x3500
	s_nop 0
	global_load_lds_dwordx4 v[160:161], off offset:768
	v_mfma_f32_32x32x16_bf16 v[18:33], v[70:73], v[74:77], v[18:33]
	s_add_u32 m0, s14, 0x4500
	s_nop 0
	global_load_lds_dwordx4 v[150:151], off offset:768
	s_add_u32 m0, s14, 0x5500
	s_nop 0
	global_load_lds_dwordx4 v[154:155], off offset:768
	v_mfma_f32_32x32x16_bf16 v[2:17], v[70:73], v[78:81], v[2:17]
	s_add_u32 m0, s14, 0x6500
	s_nop 0
	global_load_lds_dwordx4 v[158:159], off offset:768
	s_add_u32 m0, s14, 0x7500
	s_nop 0
	global_load_lds_dwordx4 v[162:163], off offset:768
	s_waitcnt vmcnt(8)
	s_barrier
	ds_read_b128 v[66:69], v130 offset:34816
	ds_read_b128 v[70:73], v130 offset:38912
	ds_read_b128 v[74:77], v134 offset:34816
	ds_read_b128 v[78:81], v134 offset:38912
	v_mfma_f32_32x32x16_bf16 v[50:65], v[82:85], v[90:93], v[50:65]
	v_mfma_f32_32x32x16_bf16 v[34:49], v[82:85], v[94:97], v[34:49]
	v_mfma_f32_32x32x16_bf16 v[18:33], v[86:89], v[90:93], v[18:33]
	v_mfma_f32_32x32x16_bf16 v[2:17], v[86:89], v[94:97], v[2:17]
	ds_read_b128 v[82:85], v131 offset:34816
	ds_read_b128 v[86:89], v131 offset:38912
	ds_read_b128 v[90:93], v135 offset:34816
	ds_read_b128 v[94:97], v135 offset:38912
	v_mfma_f32_32x32x16_bf16 v[50:65], v[98:101], v[106:109], v[50:65]
	v_mfma_f32_32x32x16_bf16 v[34:49], v[98:101], v[110:113], v[34:49]
	v_mfma_f32_32x32x16_bf16 v[18:33], v[102:105], v[106:109], v[18:33]
	v_mfma_f32_32x32x16_bf16 v[2:17], v[102:105], v[110:113], v[2:17]
	ds_read_b128 v[98:101], v132 offset:34816
	ds_read_b128 v[102:105], v132 offset:38912
	ds_read_b128 v[106:109], v136 offset:34816
	ds_read_b128 v[110:113], v136 offset:38912
	v_mfma_f32_32x32x16_bf16 v[50:65], v[114:117], v[122:125], v[50:65]
	v_mfma_f32_32x32x16_bf16 v[34:49], v[114:117], v[126:129], v[34:49]
	v_mfma_f32_32x32x16_bf16 v[18:33], v[118:121], v[122:125], v[18:33]
	v_mfma_f32_32x32x16_bf16 v[2:17], v[118:121], v[126:129], v[2:17]
	ds_read_b128 v[114:117], v133 offset:34816
	ds_read_b128 v[118:121], v133 offset:38912
	ds_read_b128 v[122:125], v137 offset:34816
	ds_read_b128 v[126:129], v137 offset:38912
	s_waitcnt lgkmcnt(0)
	s_barrier
	v_mfma_f32_32x32x16_bf16 v[50:65], v[66:69], v[74:77], v[50:65]
	s_add_u32 m0, s14, 0x8480
	s_nop 0
	global_load_lds_dwordx4 v[148:149], off offset:896
	s_add_u32 m0, s14, 0x9480
	s_nop 0
	global_load_lds_dwordx4 v[152:153], off offset:896
	v_mfma_f32_32x32x16_bf16 v[34:49], v[66:69], v[78:81], v[34:49]
	s_add_u32 m0, s14, 0xa480
	s_nop 0
	global_load_lds_dwordx4 v[156:157], off offset:896
	s_add_u32 m0, s14, 0xb480
	s_nop 0
	global_load_lds_dwordx4 v[160:161], off offset:896
	v_mfma_f32_32x32x16_bf16 v[18:33], v[70:73], v[74:77], v[18:33]
	s_add_u32 m0, s14, 0xc480
	s_nop 0
	global_load_lds_dwordx4 v[150:151], off offset:896
	s_add_u32 m0, s14, 0xd480
	s_nop 0
	global_load_lds_dwordx4 v[154:155], off offset:896
	v_mfma_f32_32x32x16_bf16 v[2:17], v[70:73], v[78:81], v[2:17]
	s_add_u32 m0, s14, 0xe480
	s_nop 0
	global_load_lds_dwordx4 v[158:159], off offset:896
	s_add_u32 m0, s14, 0xf480
	s_nop 0
	global_load_lds_dwordx4 v[162:163], off offset:896
	s_waitcnt vmcnt(8)
	s_barrier
	ds_read_b128 v[66:69], v130 offset:2048
	ds_read_b128 v[70:73], v130 offset:6144
	ds_read_b128 v[74:77], v134 offset:2048
	ds_read_b128 v[78:81], v134 offset:6144
	v_mfma_f32_32x32x16_bf16 v[50:65], v[82:85], v[90:93], v[50:65]
	v_mfma_f32_32x32x16_bf16 v[34:49], v[82:85], v[94:97], v[34:49]
	v_mfma_f32_32x32x16_bf16 v[18:33], v[86:89], v[90:93], v[18:33]
	v_mfma_f32_32x32x16_bf16 v[2:17], v[86:89], v[94:97], v[2:17]
	ds_read_b128 v[82:85], v131 offset:2048
	ds_read_b128 v[86:89], v131 offset:6144
	ds_read_b128 v[90:93], v135 offset:2048
	ds_read_b128 v[94:97], v135 offset:6144
	v_mfma_f32_32x32x16_bf16 v[50:65], v[98:101], v[106:109], v[50:65]
	v_mfma_f32_32x32x16_bf16 v[34:49], v[98:101], v[110:113], v[34:49]
	v_mfma_f32_32x32x16_bf16 v[18:33], v[102:105], v[106:109], v[18:33]
	v_mfma_f32_32x32x16_bf16 v[2:17], v[102:105], v[110:113], v[2:17]
	ds_read_b128 v[98:101], v132 offset:2048
	ds_read_b128 v[102:105], v132 offset:6144
	ds_read_b128 v[106:109], v136 offset:2048
	ds_read_b128 v[110:113], v136 offset:6144
	v_mfma_f32_32x32x16_bf16 v[50:65], v[114:117], v[122:125], v[50:65]
	v_mfma_f32_32x32x16_bf16 v[34:49], v[114:117], v[126:129], v[34:49]
	v_mfma_f32_32x32x16_bf16 v[18:33], v[118:121], v[122:125], v[18:33]
	v_mfma_f32_32x32x16_bf16 v[2:17], v[118:121], v[126:129], v[2:17]
	ds_read_b128 v[114:117], v133 offset:2048
	ds_read_b128 v[118:121], v133 offset:6144
	ds_read_b128 v[122:125], v137 offset:2048
	ds_read_b128 v[126:129], v137 offset:6144
	s_waitcnt lgkmcnt(0)
	s_barrier
	v_mfma_f32_32x32x16_bf16 v[50:65], v[66:69], v[74:77], v[50:65]
	s_add_u32 m0, s14, 0x400
	s_nop 0
	global_load_lds_dwordx4 v[148:149], off offset:1024
	s_add_u32 m0, s14, 0x1400
	s_nop 0
	global_load_lds_dwordx4 v[152:153], off offset:1024
	v_mfma_f32_32x32x16_bf16 v[34:49], v[66:69], v[78:81], v[34:49]
	s_add_u32 m0, s14, 0x2400
	s_nop 0
	global_load_lds_dwordx4 v[156:157], off offset:1024
	s_add_u32 m0, s14, 0x3400
	s_nop 0
	global_load_lds_dwordx4 v[160:161], off offset:1024
	v_mfma_f32_32x32x16_bf16 v[18:33], v[70:73], v[74:77], v[18:33]
	s_add_u32 m0, s14, 0x4400
	s_nop 0
	global_load_lds_dwordx4 v[150:151], off offset:1024
	s_add_u32 m0, s14, 0x5400
	s_nop 0
	global_load_lds_dwordx4 v[154:155], off offset:1024
	v_mfma_f32_32x32x16_bf16 v[2:17], v[70:73], v[78:81], v[2:17]
	s_add_u32 m0, s14, 0x6400
	s_nop 0
	global_load_lds_dwordx4 v[158:159], off offset:1024
	s_add_u32 m0, s14, 0x7400
	s_nop 0
	global_load_lds_dwordx4 v[162:163], off offset:1024
	s_waitcnt vmcnt(8)
	s_barrier
	ds_read_b128 v[66:69], v130 offset:34816
	ds_read_b128 v[70:73], v130 offset:38912
	ds_read_b128 v[74:77], v134 offset:34816
	ds_read_b128 v[78:81], v134 offset:38912
	v_mfma_f32_32x32x16_bf16 v[50:65], v[82:85], v[90:93], v[50:65]
	v_mfma_f32_32x32x16_bf16 v[34:49], v[82:85], v[94:97], v[34:49]
	v_mfma_f32_32x32x16_bf16 v[18:33], v[86:89], v[90:93], v[18:33]
	v_mfma_f32_32x32x16_bf16 v[2:17], v[86:89], v[94:97], v[2:17]
	ds_read_b128 v[82:85], v131 offset:34816
	ds_read_b128 v[86:89], v131 offset:38912
	ds_read_b128 v[90:93], v135 offset:34816
	ds_read_b128 v[94:97], v135 offset:38912
	v_mfma_f32_32x32x16_bf16 v[50:65], v[98:101], v[106:109], v[50:65]
	v_mfma_f32_32x32x16_bf16 v[34:49], v[98:101], v[110:113], v[34:49]
	v_mfma_f32_32x32x16_bf16 v[18:33], v[102:105], v[106:109], v[18:33]
	v_mfma_f32_32x32x16_bf16 v[2:17], v[102:105], v[110:113], v[2:17]
	ds_read_b128 v[98:101], v132 offset:34816
	ds_read_b128 v[102:105], v132 offset:38912
	ds_read_b128 v[106:109], v136 offset:34816
	ds_read_b128 v[110:113], v136 offset:38912
	v_mfma_f32_32x32x16_bf16 v[50:65], v[114:117], v[122:125], v[50:65]
	v_mfma_f32_32x32x16_bf16 v[34:49], v[114:117], v[126:129], v[34:49]
	v_mfma_f32_32x32x16_bf16 v[18:33], v[118:121], v[122:125], v[18:33]
	v_mfma_f32_32x32x16_bf16 v[2:17], v[118:121], v[126:129], v[2:17]
	ds_read_b128 v[114:117], v133 offset:34816
	ds_read_b128 v[118:121], v133 offset:38912
	ds_read_b128 v[122:125], v137 offset:34816
	ds_read_b128 v[126:129], v137 offset:38912
	s_waitcnt lgkmcnt(0)
	s_barrier
	v_mfma_f32_32x32x16_bf16 v[50:65], v[66:69], v[74:77], v[50:65]
	s_add_u32 m0, s14, 0x8380
	s_nop 0
	global_load_lds_dwordx4 v[148:149], off offset:1152
	s_add_u32 m0, s14, 0x9380
	s_nop 0
	global_load_lds_dwordx4 v[152:153], off offset:1152
	v_mfma_f32_32x32x16_bf16 v[34:49], v[66:69], v[78:81], v[34:49]
	s_add_u32 m0, s14, 0xa380
	s_nop 0
	global_load_lds_dwordx4 v[156:157], off offset:1152
	s_add_u32 m0, s14, 0xb380
	s_nop 0
	global_load_lds_dwordx4 v[160:161], off offset:1152
	v_mfma_f32_32x32x16_bf16 v[18:33], v[70:73], v[74:77], v[18:33]
	s_add_u32 m0, s14, 0xc380
	s_nop 0
	global_load_lds_dwordx4 v[150:151], off offset:1152
	s_add_u32 m0, s14, 0xd380
	s_nop 0
	global_load_lds_dwordx4 v[154:155], off offset:1152
	v_mfma_f32_32x32x16_bf16 v[2:17], v[70:73], v[78:81], v[2:17]
	s_add_u32 m0, s14, 0xe380
	s_nop 0
	global_load_lds_dwordx4 v[158:159], off offset:1152
	s_add_u32 m0, s14, 0xf380
	s_nop 0
	global_load_lds_dwordx4 v[162:163], off offset:1152
	s_waitcnt vmcnt(8)
	s_barrier
	ds_read_b128 v[66:69], v130 offset:2048
	ds_read_b128 v[70:73], v130 offset:6144
	ds_read_b128 v[74:77], v134 offset:2048
	ds_read_b128 v[78:81], v134 offset:6144
	v_mfma_f32_32x32x16_bf16 v[50:65], v[82:85], v[90:93], v[50:65]
	v_mfma_f32_32x32x16_bf16 v[34:49], v[82:85], v[94:97], v[34:49]
	v_mfma_f32_32x32x16_bf16 v[18:33], v[86:89], v[90:93], v[18:33]
	v_mfma_f32_32x32x16_bf16 v[2:17], v[86:89], v[94:97], v[2:17]
	ds_read_b128 v[82:85], v131 offset:2048
	ds_read_b128 v[86:89], v131 offset:6144
	ds_read_b128 v[90:93], v135 offset:2048
	ds_read_b128 v[94:97], v135 offset:6144
	v_mfma_f32_32x32x16_bf16 v[50:65], v[98:101], v[106:109], v[50:65]
	v_mfma_f32_32x32x16_bf16 v[34:49], v[98:101], v[110:113], v[34:49]
	v_mfma_f32_32x32x16_bf16 v[18:33], v[102:105], v[106:109], v[18:33]
	v_mfma_f32_32x32x16_bf16 v[2:17], v[102:105], v[110:113], v[2:17]
	ds_read_b128 v[98:101], v132 offset:2048
	ds_read_b128 v[102:105], v132 offset:6144
	ds_read_b128 v[106:109], v136 offset:2048
	ds_read_b128 v[110:113], v136 offset:6144
	v_mfma_f32_32x32x16_bf16 v[50:65], v[114:117], v[122:125], v[50:65]
	v_mfma_f32_32x32x16_bf16 v[34:49], v[114:117], v[126:129], v[34:49]
	v_mfma_f32_32x32x16_bf16 v[18:33], v[118:121], v[122:125], v[18:33]
	v_mfma_f32_32x32x16_bf16 v[2:17], v[118:121], v[126:129], v[2:17]
	ds_read_b128 v[114:117], v133 offset:2048
	ds_read_b128 v[118:121], v133 offset:6144
	ds_read_b128 v[122:125], v137 offset:2048
	ds_read_b128 v[126:129], v137 offset:6144
	s_waitcnt lgkmcnt(0)
	s_barrier
	v_mfma_f32_32x32x16_bf16 v[50:65], v[66:69], v[74:77], v[50:65]
	s_add_u32 m0, s14, 0x300
	s_nop 0
	global_load_lds_dwordx4 v[148:149], off offset:1280
	s_add_u32 m0, s14, 0x1300
	s_nop 0
	global_load_lds_dwordx4 v[152:153], off offset:1280
	v_mfma_f32_32x32x16_bf16 v[34:49], v[66:69], v[78:81], v[34:49]
	s_add_u32 m0, s14, 0x2300
	s_nop 0
	global_load_lds_dwordx4 v[156:157], off offset:1280
	s_add_u32 m0, s14, 0x3300
	s_nop 0
	global_load_lds_dwordx4 v[160:161], off offset:1280
	v_mfma_f32_32x32x16_bf16 v[18:33], v[70:73], v[74:77], v[18:33]
	s_add_u32 m0, s14, 0x4300
	s_nop 0
	global_load_lds_dwordx4 v[150:151], off offset:1280
	s_add_u32 m0, s14, 0x5300
	s_nop 0
	global_load_lds_dwordx4 v[154:155], off offset:1280
	v_mfma_f32_32x32x16_bf16 v[2:17], v[70:73], v[78:81], v[2:17]
	s_add_u32 m0, s14, 0x6300
	s_nop 0
	global_load_lds_dwordx4 v[158:159], off offset:1280
	s_add_u32 m0, s14, 0x7300
	s_nop 0
	global_load_lds_dwordx4 v[162:163], off offset:1280
	s_waitcnt vmcnt(8)
	s_barrier
	ds_read_b128 v[66:69], v130 offset:34816
	ds_read_b128 v[70:73], v130 offset:38912
	ds_read_b128 v[74:77], v134 offset:34816
	ds_read_b128 v[78:81], v134 offset:38912
	v_mfma_f32_32x32x16_bf16 v[50:65], v[82:85], v[90:93], v[50:65]
	v_mfma_f32_32x32x16_bf16 v[34:49], v[82:85], v[94:97], v[34:49]
	v_mfma_f32_32x32x16_bf16 v[18:33], v[86:89], v[90:93], v[18:33]
	v_mfma_f32_32x32x16_bf16 v[2:17], v[86:89], v[94:97], v[2:17]
	ds_read_b128 v[82:85], v131 offset:34816
	ds_read_b128 v[86:89], v131 offset:38912
	ds_read_b128 v[90:93], v135 offset:34816
	ds_read_b128 v[94:97], v135 offset:38912
	v_mfma_f32_32x32x16_bf16 v[50:65], v[98:101], v[106:109], v[50:65]
	v_mfma_f32_32x32x16_bf16 v[34:49], v[98:101], v[110:113], v[34:49]
	v_mfma_f32_32x32x16_bf16 v[18:33], v[102:105], v[106:109], v[18:33]
	v_mfma_f32_32x32x16_bf16 v[2:17], v[102:105], v[110:113], v[2:17]
	ds_read_b128 v[98:101], v132 offset:34816
	ds_read_b128 v[102:105], v132 offset:38912
	ds_read_b128 v[106:109], v136 offset:34816
	ds_read_b128 v[110:113], v136 offset:38912
	v_mfma_f32_32x32x16_bf16 v[50:65], v[114:117], v[122:125], v[50:65]
	v_mfma_f32_32x32x16_bf16 v[34:49], v[114:117], v[126:129], v[34:49]
	v_mfma_f32_32x32x16_bf16 v[18:33], v[118:121], v[122:125], v[18:33]
	v_mfma_f32_32x32x16_bf16 v[2:17], v[118:121], v[126:129], v[2:17]
	ds_read_b128 v[114:117], v133 offset:34816
	ds_read_b128 v[118:121], v133 offset:38912
	ds_read_b128 v[122:125], v137 offset:34816
	ds_read_b128 v[126:129], v137 offset:38912
	s_waitcnt lgkmcnt(0)
	s_barrier
	v_mfma_f32_32x32x16_bf16 v[50:65], v[66:69], v[74:77], v[50:65]
	s_add_u32 m0, s14, 0x8280
	s_nop 0
	global_load_lds_dwordx4 v[148:149], off offset:1408
	s_add_u32 m0, s14, 0x9280
	s_nop 0
	global_load_lds_dwordx4 v[152:153], off offset:1408
	v_mfma_f32_32x32x16_bf16 v[34:49], v[66:69], v[78:81], v[34:49]
	s_add_u32 m0, s14, 0xa280
	s_nop 0
	global_load_lds_dwordx4 v[156:157], off offset:1408
	s_add_u32 m0, s14, 0xb280
	s_nop 0
	global_load_lds_dwordx4 v[160:161], off offset:1408
	v_mfma_f32_32x32x16_bf16 v[18:33], v[70:73], v[74:77], v[18:33]
	s_add_u32 m0, s14, 0xc280
	s_nop 0
	global_load_lds_dwordx4 v[150:151], off offset:1408
	s_add_u32 m0, s14, 0xd280
	s_nop 0
	global_load_lds_dwordx4 v[154:155], off offset:1408
	v_mfma_f32_32x32x16_bf16 v[2:17], v[70:73], v[78:81], v[2:17]
	s_add_u32 m0, s14, 0xe280
	s_nop 0
	global_load_lds_dwordx4 v[158:159], off offset:1408
	s_add_u32 m0, s14, 0xf280
	s_nop 0
	global_load_lds_dwordx4 v[162:163], off offset:1408
	s_waitcnt vmcnt(8)
	s_barrier
	ds_read_b128 v[66:69], v130 offset:2048
	ds_read_b128 v[70:73], v130 offset:6144
	ds_read_b128 v[74:77], v134 offset:2048
	ds_read_b128 v[78:81], v134 offset:6144
	v_mfma_f32_32x32x16_bf16 v[50:65], v[82:85], v[90:93], v[50:65]
	v_mfma_f32_32x32x16_bf16 v[34:49], v[82:85], v[94:97], v[34:49]
	v_mfma_f32_32x32x16_bf16 v[18:33], v[86:89], v[90:93], v[18:33]
	v_mfma_f32_32x32x16_bf16 v[2:17], v[86:89], v[94:97], v[2:17]
	ds_read_b128 v[82:85], v131 offset:2048
	ds_read_b128 v[86:89], v131 offset:6144
	ds_read_b128 v[90:93], v135 offset:2048
	ds_read_b128 v[94:97], v135 offset:6144
	v_mfma_f32_32x32x16_bf16 v[50:65], v[98:101], v[106:109], v[50:65]
	v_mfma_f32_32x32x16_bf16 v[34:49], v[98:101], v[110:113], v[34:49]
	v_mfma_f32_32x32x16_bf16 v[18:33], v[102:105], v[106:109], v[18:33]
	v_mfma_f32_32x32x16_bf16 v[2:17], v[102:105], v[110:113], v[2:17]
	ds_read_b128 v[98:101], v132 offset:2048
	ds_read_b128 v[102:105], v132 offset:6144
	ds_read_b128 v[106:109], v136 offset:2048
	ds_read_b128 v[110:113], v136 offset:6144
	v_mfma_f32_32x32x16_bf16 v[50:65], v[114:117], v[122:125], v[50:65]
	v_mfma_f32_32x32x16_bf16 v[34:49], v[114:117], v[126:129], v[34:49]
	v_mfma_f32_32x32x16_bf16 v[18:33], v[118:121], v[122:125], v[18:33]
	v_mfma_f32_32x32x16_bf16 v[2:17], v[118:121], v[126:129], v[2:17]
	ds_read_b128 v[114:117], v133 offset:2048
	ds_read_b128 v[118:121], v133 offset:6144
	ds_read_b128 v[122:125], v137 offset:2048
	ds_read_b128 v[126:129], v137 offset:6144
	s_waitcnt lgkmcnt(0)
	s_barrier
	v_mfma_f32_32x32x16_bf16 v[50:65], v[66:69], v[74:77], v[50:65]
	s_add_u32 m0, s14, 0x200
	s_nop 0
	global_load_lds_dwordx4 v[148:149], off offset:1536
	s_add_u32 m0, s14, 0x1200
	s_nop 0
	global_load_lds_dwordx4 v[152:153], off offset:1536
	v_mfma_f32_32x32x16_bf16 v[34:49], v[66:69], v[78:81], v[34:49]
	s_add_u32 m0, s14, 0x2200
	s_nop 0
	global_load_lds_dwordx4 v[156:157], off offset:1536
	s_add_u32 m0, s14, 0x3200
	s_nop 0
	global_load_lds_dwordx4 v[160:161], off offset:1536
	v_mfma_f32_32x32x16_bf16 v[18:33], v[70:73], v[74:77], v[18:33]
	s_add_u32 m0, s14, 0x4200
	s_nop 0
	global_load_lds_dwordx4 v[150:151], off offset:1536
	s_add_u32 m0, s14, 0x5200
	s_nop 0
	global_load_lds_dwordx4 v[154:155], off offset:1536
	v_mfma_f32_32x32x16_bf16 v[2:17], v[70:73], v[78:81], v[2:17]
	s_add_u32 m0, s14, 0x6200
	s_nop 0
	global_load_lds_dwordx4 v[158:159], off offset:1536
	s_add_u32 m0, s14, 0x7200
	s_nop 0
	global_load_lds_dwordx4 v[162:163], off offset:1536
	s_waitcnt vmcnt(8)
	s_barrier
	ds_read_b128 v[66:69], v130 offset:34816
	ds_read_b128 v[70:73], v130 offset:38912
	ds_read_b128 v[74:77], v134 offset:34816
	ds_read_b128 v[78:81], v134 offset:38912
	v_mfma_f32_32x32x16_bf16 v[50:65], v[82:85], v[90:93], v[50:65]
	v_mfma_f32_32x32x16_bf16 v[34:49], v[82:85], v[94:97], v[34:49]
	v_mfma_f32_32x32x16_bf16 v[18:33], v[86:89], v[90:93], v[18:33]
	v_mfma_f32_32x32x16_bf16 v[2:17], v[86:89], v[94:97], v[2:17]
	ds_read_b128 v[82:85], v131 offset:34816
	ds_read_b128 v[86:89], v131 offset:38912
	ds_read_b128 v[90:93], v135 offset:34816
	ds_read_b128 v[94:97], v135 offset:38912
	v_mfma_f32_32x32x16_bf16 v[50:65], v[98:101], v[106:109], v[50:65]
	v_mfma_f32_32x32x16_bf16 v[34:49], v[98:101], v[110:113], v[34:49]
	v_mfma_f32_32x32x16_bf16 v[18:33], v[102:105], v[106:109], v[18:33]
	v_mfma_f32_32x32x16_bf16 v[2:17], v[102:105], v[110:113], v[2:17]
	ds_read_b128 v[98:101], v132 offset:34816
	ds_read_b128 v[102:105], v132 offset:38912
	ds_read_b128 v[106:109], v136 offset:34816
	ds_read_b128 v[110:113], v136 offset:38912
	v_mfma_f32_32x32x16_bf16 v[50:65], v[114:117], v[122:125], v[50:65]
	v_mfma_f32_32x32x16_bf16 v[34:49], v[114:117], v[126:129], v[34:49]
	v_mfma_f32_32x32x16_bf16 v[18:33], v[118:121], v[122:125], v[18:33]
	v_mfma_f32_32x32x16_bf16 v[2:17], v[118:121], v[126:129], v[2:17]
	ds_read_b128 v[114:117], v133 offset:34816
	ds_read_b128 v[118:121], v133 offset:38912
	ds_read_b128 v[122:125], v137 offset:34816
	ds_read_b128 v[126:129], v137 offset:38912
	s_waitcnt lgkmcnt(0)
	s_barrier
	v_mfma_f32_32x32x16_bf16 v[50:65], v[66:69], v[74:77], v[50:65]
	s_add_u32 m0, s14, 0x8180
	s_nop 0
	global_load_lds_dwordx4 v[148:149], off offset:1664
	s_add_u32 m0, s14, 0x9180
	s_nop 0
	global_load_lds_dwordx4 v[152:153], off offset:1664
	v_mfma_f32_32x32x16_bf16 v[34:49], v[66:69], v[78:81], v[34:49]
	s_add_u32 m0, s14, 0xa180
	s_nop 0
	global_load_lds_dwordx4 v[156:157], off offset:1664
	s_add_u32 m0, s14, 0xb180
	s_nop 0
	global_load_lds_dwordx4 v[160:161], off offset:1664
	v_mfma_f32_32x32x16_bf16 v[18:33], v[70:73], v[74:77], v[18:33]
	s_add_u32 m0, s14, 0xc180
	s_nop 0
	global_load_lds_dwordx4 v[150:151], off offset:1664
	s_add_u32 m0, s14, 0xd180
	s_nop 0
	global_load_lds_dwordx4 v[154:155], off offset:1664
	v_mfma_f32_32x32x16_bf16 v[2:17], v[70:73], v[78:81], v[2:17]
	s_add_u32 m0, s14, 0xe180
	s_nop 0
	global_load_lds_dwordx4 v[158:159], off offset:1664
	s_add_u32 m0, s14, 0xf180
	s_nop 0
	global_load_lds_dwordx4 v[162:163], off offset:1664
	s_waitcnt vmcnt(8)
	s_barrier
	ds_read_b128 v[66:69], v130 offset:2048
	ds_read_b128 v[70:73], v130 offset:6144
	ds_read_b128 v[74:77], v134 offset:2048
	ds_read_b128 v[78:81], v134 offset:6144
	v_mfma_f32_32x32x16_bf16 v[50:65], v[82:85], v[90:93], v[50:65]
	v_mfma_f32_32x32x16_bf16 v[34:49], v[82:85], v[94:97], v[34:49]
	v_mfma_f32_32x32x16_bf16 v[18:33], v[86:89], v[90:93], v[18:33]
	v_mfma_f32_32x32x16_bf16 v[2:17], v[86:89], v[94:97], v[2:17]
	ds_read_b128 v[82:85], v131 offset:2048
	ds_read_b128 v[86:89], v131 offset:6144
	ds_read_b128 v[90:93], v135 offset:2048
	ds_read_b128 v[94:97], v135 offset:6144
	v_mfma_f32_32x32x16_bf16 v[50:65], v[98:101], v[106:109], v[50:65]
	v_mfma_f32_32x32x16_bf16 v[34:49], v[98:101], v[110:113], v[34:49]
	v_mfma_f32_32x32x16_bf16 v[18:33], v[102:105], v[106:109], v[18:33]
	v_mfma_f32_32x32x16_bf16 v[2:17], v[102:105], v[110:113], v[2:17]
	ds_read_b128 v[98:101], v132 offset:2048
	ds_read_b128 v[102:105], v132 offset:6144
	ds_read_b128 v[106:109], v136 offset:2048
	ds_read_b128 v[110:113], v136 offset:6144
	v_mfma_f32_32x32x16_bf16 v[50:65], v[114:117], v[122:125], v[50:65]
	v_mfma_f32_32x32x16_bf16 v[34:49], v[114:117], v[126:129], v[34:49]
	v_mfma_f32_32x32x16_bf16 v[18:33], v[118:121], v[122:125], v[18:33]
	v_mfma_f32_32x32x16_bf16 v[2:17], v[118:121], v[126:129], v[2:17]
	ds_read_b128 v[114:117], v133 offset:2048
	ds_read_b128 v[118:121], v133 offset:6144
	ds_read_b128 v[122:125], v137 offset:2048
	ds_read_b128 v[126:129], v137 offset:6144
	s_waitcnt lgkmcnt(0)
	s_barrier
	v_mfma_f32_32x32x16_bf16 v[50:65], v[66:69], v[74:77], v[50:65]
	s_add_u32 m0, s14, 0x100
	s_nop 0
	global_load_lds_dwordx4 v[148:149], off offset:1792
	s_add_u32 m0, s14, 0x1100
	s_nop 0
	global_load_lds_dwordx4 v[152:153], off offset:1792
	v_mfma_f32_32x32x16_bf16 v[34:49], v[66:69], v[78:81], v[34:49]
	s_add_u32 m0, s14, 0x2100
	s_nop 0
	global_load_lds_dwordx4 v[156:157], off offset:1792
	s_add_u32 m0, s14, 0x3100
	s_nop 0
	global_load_lds_dwordx4 v[160:161], off offset:1792
	v_mfma_f32_32x32x16_bf16 v[18:33], v[70:73], v[74:77], v[18:33]
	s_add_u32 m0, s14, 0x4100
	s_nop 0
	global_load_lds_dwordx4 v[150:151], off offset:1792
	s_add_u32 m0, s14, 0x5100
	s_nop 0
	global_load_lds_dwordx4 v[154:155], off offset:1792
	v_mfma_f32_32x32x16_bf16 v[2:17], v[70:73], v[78:81], v[2:17]
	s_add_u32 m0, s14, 0x6100
	s_nop 0
	global_load_lds_dwordx4 v[158:159], off offset:1792
	s_add_u32 m0, s14, 0x7100
	s_nop 0
	global_load_lds_dwordx4 v[162:163], off offset:1792
	s_waitcnt vmcnt(8)
	s_barrier
	ds_read_b128 v[66:69], v130 offset:34816
	ds_read_b128 v[70:73], v130 offset:38912
	ds_read_b128 v[74:77], v134 offset:34816
	ds_read_b128 v[78:81], v134 offset:38912
	v_mfma_f32_32x32x16_bf16 v[50:65], v[82:85], v[90:93], v[50:65]
	v_mfma_f32_32x32x16_bf16 v[34:49], v[82:85], v[94:97], v[34:49]
	v_mfma_f32_32x32x16_bf16 v[18:33], v[86:89], v[90:93], v[18:33]
	v_mfma_f32_32x32x16_bf16 v[2:17], v[86:89], v[94:97], v[2:17]
	ds_read_b128 v[82:85], v131 offset:34816
	ds_read_b128 v[86:89], v131 offset:38912
	ds_read_b128 v[90:93], v135 offset:34816
	ds_read_b128 v[94:97], v135 offset:38912
	v_mfma_f32_32x32x16_bf16 v[50:65], v[98:101], v[106:109], v[50:65]
	v_mfma_f32_32x32x16_bf16 v[34:49], v[98:101], v[110:113], v[34:49]
	v_mfma_f32_32x32x16_bf16 v[18:33], v[102:105], v[106:109], v[18:33]
	v_mfma_f32_32x32x16_bf16 v[2:17], v[102:105], v[110:113], v[2:17]
	ds_read_b128 v[98:101], v132 offset:34816
	ds_read_b128 v[102:105], v132 offset:38912
	ds_read_b128 v[106:109], v136 offset:34816
	ds_read_b128 v[110:113], v136 offset:38912
	v_mfma_f32_32x32x16_bf16 v[50:65], v[114:117], v[122:125], v[50:65]
	v_mfma_f32_32x32x16_bf16 v[34:49], v[114:117], v[126:129], v[34:49]
	v_mfma_f32_32x32x16_bf16 v[18:33], v[118:121], v[122:125], v[18:33]
	v_mfma_f32_32x32x16_bf16 v[2:17], v[118:121], v[126:129], v[2:17]
	ds_read_b128 v[114:117], v133 offset:34816
	ds_read_b128 v[118:121], v133 offset:38912
	ds_read_b128 v[122:125], v137 offset:34816
	ds_read_b128 v[126:129], v137 offset:38912
	s_waitcnt lgkmcnt(0)
	s_barrier
	v_mfma_f32_32x32x16_bf16 v[50:65], v[66:69], v[74:77], v[50:65]
	s_add_u32 m0, s14, 0x8080
	s_nop 0
	global_load_lds_dwordx4 v[148:149], off offset:1920
	s_add_u32 m0, s14, 0x9080
	s_nop 0
	global_load_lds_dwordx4 v[152:153], off offset:1920
	v_mfma_f32_32x32x16_bf16 v[34:49], v[66:69], v[78:81], v[34:49]
	s_add_u32 m0, s14, 0xa080
	s_nop 0
	global_load_lds_dwordx4 v[156:157], off offset:1920
	s_add_u32 m0, s14, 0xb080
	s_nop 0
	global_load_lds_dwordx4 v[160:161], off offset:1920
	v_mfma_f32_32x32x16_bf16 v[18:33], v[70:73], v[74:77], v[18:33]
	s_add_u32 m0, s14, 0xc080
	s_nop 0
	global_load_lds_dwordx4 v[150:151], off offset:1920
	s_add_u32 m0, s14, 0xd080
	s_nop 0
	global_load_lds_dwordx4 v[154:155], off offset:1920
	v_mfma_f32_32x32x16_bf16 v[2:17], v[70:73], v[78:81], v[2:17]
	s_add_u32 m0, s14, 0xe080
	s_nop 0
	global_load_lds_dwordx4 v[158:159], off offset:1920
	s_add_u32 m0, s14, 0xf080
	s_nop 0
	global_load_lds_dwordx4 v[162:163], off offset:1920
	s_waitcnt vmcnt(8)
	s_barrier
	ds_read_b128 v[66:69], v130 offset:2048
	ds_read_b128 v[70:73], v130 offset:6144
	ds_read_b128 v[74:77], v134 offset:2048
	ds_read_b128 v[78:81], v134 offset:6144
	v_mfma_f32_32x32x16_bf16 v[50:65], v[82:85], v[90:93], v[50:65]
	v_mfma_f32_32x32x16_bf16 v[34:49], v[82:85], v[94:97], v[34:49]
	v_mfma_f32_32x32x16_bf16 v[18:33], v[86:89], v[90:93], v[18:33]
	v_mfma_f32_32x32x16_bf16 v[2:17], v[86:89], v[94:97], v[2:17]
	ds_read_b128 v[82:85], v131 offset:2048
	ds_read_b128 v[86:89], v131 offset:6144
	ds_read_b128 v[90:93], v135 offset:2048
	ds_read_b128 v[94:97], v135 offset:6144
	v_mfma_f32_32x32x16_bf16 v[50:65], v[98:101], v[106:109], v[50:65]
	v_mfma_f32_32x32x16_bf16 v[34:49], v[98:101], v[110:113], v[34:49]
	v_mfma_f32_32x32x16_bf16 v[18:33], v[102:105], v[106:109], v[18:33]
	v_mfma_f32_32x32x16_bf16 v[2:17], v[102:105], v[110:113], v[2:17]
	ds_read_b128 v[98:101], v132 offset:2048
	ds_read_b128 v[102:105], v132 offset:6144
	ds_read_b128 v[106:109], v136 offset:2048
	ds_read_b128 v[110:113], v136 offset:6144
	v_mfma_f32_32x32x16_bf16 v[50:65], v[114:117], v[122:125], v[50:65]
	v_mfma_f32_32x32x16_bf16 v[34:49], v[114:117], v[126:129], v[34:49]
	v_mfma_f32_32x32x16_bf16 v[18:33], v[118:121], v[122:125], v[18:33]
	v_mfma_f32_32x32x16_bf16 v[2:17], v[118:121], v[126:129], v[2:17]
	ds_read_b128 v[114:117], v133 offset:2048
	ds_read_b128 v[118:121], v133 offset:6144
	ds_read_b128 v[122:125], v137 offset:2048
	ds_read_b128 v[126:129], v137 offset:6144
	s_waitcnt lgkmcnt(0)
	v_mfma_f32_32x32x16_bf16 v[50:65], v[66:69], v[74:77], v[50:65]
	v_mfma_f32_32x32x16_bf16 v[34:49], v[66:69], v[78:81], v[34:49]
	v_mfma_f32_32x32x16_bf16 v[18:33], v[70:73], v[74:77], v[18:33]
	v_mfma_f32_32x32x16_bf16 v[2:17], v[70:73], v[78:81], v[2:17]
	s_waitcnt vmcnt(0)
	s_barrier
	ds_read_b128 v[66:69], v130 offset:34816
	ds_read_b128 v[70:73], v130 offset:38912
	ds_read_b128 v[74:77], v134 offset:34816
	ds_read_b128 v[78:81], v134 offset:38912
	v_mfma_f32_32x32x16_bf16 v[50:65], v[82:85], v[90:93], v[50:65]
	v_mfma_f32_32x32x16_bf16 v[34:49], v[82:85], v[94:97], v[34:49]
	v_mfma_f32_32x32x16_bf16 v[18:33], v[86:89], v[90:93], v[18:33]
	v_mfma_f32_32x32x16_bf16 v[2:17], v[86:89], v[94:97], v[2:17]
	ds_read_b128 v[82:85], v131 offset:34816
	ds_read_b128 v[86:89], v131 offset:38912
	ds_read_b128 v[90:93], v135 offset:34816
	ds_read_b128 v[94:97], v135 offset:38912
	v_mfma_f32_32x32x16_bf16 v[50:65], v[98:101], v[106:109], v[50:65]
	v_mfma_f32_32x32x16_bf16 v[34:49], v[98:101], v[110:113], v[34:49]
	v_mfma_f32_32x32x16_bf16 v[18:33], v[102:105], v[106:109], v[18:33]
	v_mfma_f32_32x32x16_bf16 v[2:17], v[102:105], v[110:113], v[2:17]
	ds_read_b128 v[98:101], v132 offset:34816
	ds_read_b128 v[102:105], v132 offset:38912
	ds_read_b128 v[106:109], v136 offset:34816
	ds_read_b128 v[110:113], v136 offset:38912
	v_mfma_f32_32x32x16_bf16 v[50:65], v[114:117], v[122:125], v[50:65]
	v_mfma_f32_32x32x16_bf16 v[34:49], v[114:117], v[126:129], v[34:49]
	v_mfma_f32_32x32x16_bf16 v[18:33], v[118:121], v[122:125], v[18:33]
	v_mfma_f32_32x32x16_bf16 v[2:17], v[118:121], v[126:129], v[2:17]
	ds_read_b128 v[114:117], v133 offset:34816
	ds_read_b128 v[118:121], v133 offset:38912
	ds_read_b128 v[122:125], v137 offset:34816
	ds_read_b128 v[126:129], v137 offset:38912
	s_waitcnt lgkmcnt(0)
	v_mfma_f32_32x32x16_bf16 v[50:65], v[66:69], v[74:77], v[50:65]
	v_mfma_f32_32x32x16_bf16 v[34:49], v[66:69], v[78:81], v[34:49]
	v_mfma_f32_32x32x16_bf16 v[18:33], v[70:73], v[74:77], v[18:33]
	v_mfma_f32_32x32x16_bf16 v[2:17], v[70:73], v[78:81], v[2:17]
	v_mfma_f32_32x32x16_bf16 v[50:65], v[82:85], v[90:93], v[50:65]
	v_mfma_f32_32x32x16_bf16 v[34:49], v[82:85], v[94:97], v[34:49]
	v_mfma_f32_32x32x16_bf16 v[18:33], v[86:89], v[90:93], v[18:33]
	v_mfma_f32_32x32x16_bf16 v[2:17], v[86:89], v[94:97], v[2:17]
	v_mfma_f32_32x32x16_bf16 v[50:65], v[98:101], v[106:109], v[50:65]
	v_mfma_f32_32x32x16_bf16 v[34:49], v[98:101], v[110:113], v[34:49]
	v_mfma_f32_32x32x16_bf16 v[18:33], v[102:105], v[106:109], v[18:33]
	v_mfma_f32_32x32x16_bf16 v[2:17], v[102:105], v[110:113], v[2:17]
	v_mfma_f32_32x32x16_bf16 v[50:65], v[114:117], v[122:125], v[50:65]
	v_mfma_f32_32x32x16_bf16 v[34:49], v[114:117], v[126:129], v[34:49]
	v_mfma_f32_32x32x16_bf16 v[18:33], v[118:121], v[122:125], v[18:33]
	v_mfma_f32_32x32x16_bf16 v[2:17], v[118:121], v[126:129], v[2:17]
	s_setprio 0
	s_cmp_eq_u32 s45, 1
	s_waitcnt lgkmcnt(0)
	s_barrier
	s_cmp_eq_u32 s45, 1
	s_movk_i32 s15, 0xaa0
	s_cselect_b32 s16, s15, 0x12a0
	s_mov_b32 s15, 0x12f0000
	s_cselect_b32 s17, s15, 0x13f0000
	s_cmp_eq_u32 s45, 0
	s_cselect_b32 s16, 0x2a0, s16
	s_cselect_b32 s17, 0x11f0000, s17
	s_lshl_b32 s16, s16, 1
	v_mov_b32_e32 v86, s43
	v_mov_b32_e32 v87, s44
	v_add_co_u32_e32 v86, vcc, s16, v86
	s_nop 1
	v_addc_co_u32_e32 v87, vcc, 0, v87, vcc
	v_mov_b32_e32 v88, s25
	v_mov_b32_e32 v89, s42
	v_add_co_u32_e32 v88, vcc, s17, v88
	s_nop 1
	v_addc_co_u32_e32 v89, vcc, 0, v89, vcc
	v_lshrrev_b32_e32 v90, 3, v178
	v_and_b32_e32 v91, 7, v178
	v_bfe_u32 v92, v178, 4, 3
	v_xor_b32_e32 v91, v91, v92
	v_lshlrev_b32_e32 v91, 4, v91
	v_mul_lo_u32 v92, v90, s77
	v_add_u32_e32 v92, v92, v91
	v_mov_b32_e32 v93, 0
	v_lshl_add_u64 v[70:71], v[86:87], 0, v[92:93]
	v_lshl_add_u32 v92, v90, 10, v91
	v_lshl_add_u64 v[78:79], v[88:89], 0, v[92:93]
	s_mov_b32 s15, 0x18000
	v_add_co_u32_e32 v72, vcc, s97, v70
	s_nop 1
	v_addc_co_u32_e32 v73, vcc, 0, v71, vcc
	v_add_co_u32_e32 v80, vcc, s31, v78
	s_nop 1
	v_addc_co_u32_e32 v81, vcc, 0, v79, vcc
	v_add_co_u32_e32 v74, vcc, s26, v70
	s_nop 1
	v_addc_co_u32_e32 v75, vcc, 0, v71, vcc
	v_add_co_u32_e32 v82, vcc, s73, v78
	s_nop 1
	v_addc_co_u32_e32 v83, vcc, 0, v79, vcc
	v_add_co_u32_e32 v76, vcc, s96, v70
	s_nop 1
	v_addc_co_u32_e32 v77, vcc, 0, v71, vcc
	v_add_co_u32_e32 v84, vcc, s15, v78
	s_nop 1
	v_addc_co_u32_e32 v85, vcc, 0, v79, vcc
	s_add_u32 m0, s14, 0x800
	s_nop 0
	global_load_lds_dwordx4 v[70:71], off
	s_add_u32 m0, s14, 0x1800
	s_nop 0
	global_load_lds_dwordx4 v[72:73], off
	s_add_u32 m0, s14, 0x2800
	s_nop 0
	global_load_lds_dwordx4 v[74:75], off
	s_add_u32 m0, s14, 0x3800
	s_nop 0
	global_load_lds_dwordx4 v[76:77], off
	s_add_u32 m0, s14, 0x4800
	s_nop 0
	global_load_lds_dwordx4 v[78:79], off
	s_add_u32 m0, s14, 0x5800
	s_nop 0
	global_load_lds_dwordx4 v[80:81], off
	s_add_u32 m0, s14, 0x6800
	s_nop 0
	global_load_lds_dwordx4 v[82:83], off
	s_add_u32 m0, s14, 0x7800
	s_nop 0
	global_load_lds_dwordx4 v[84:85], off
	s_add_u32 m0, s14, 0x8780
	s_nop 0
	global_load_lds_dwordx4 v[70:71], off offset:128
	s_add_u32 m0, s14, 0x9780
	s_nop 0
	global_load_lds_dwordx4 v[72:73], off offset:128
	s_add_u32 m0, s14, 0xa780
	s_nop 0
	global_load_lds_dwordx4 v[74:75], off offset:128
	s_add_u32 m0, s14, 0xb780
	s_nop 0
	global_load_lds_dwordx4 v[76:77], off offset:128
	s_add_u32 m0, s14, 0xc780
	s_nop 0
	global_load_lds_dwordx4 v[78:79], off offset:128
	s_add_u32 m0, s14, 0xd780
	s_nop 0
	global_load_lds_dwordx4 v[80:81], off offset:128
	s_add_u32 m0, s14, 0xe780
	s_nop 0
	global_load_lds_dwordx4 v[82:83], off offset:128
	s_add_u32 m0, s14, 0xf780
	s_nop 0
	global_load_lds_dwordx4 v[84:85], off offset:128
	s_cmp_eq_u32 s45, 1
	s_nop 0
	s_nop 0
	s_nop 10
	v_mul_f32_e32 v0, 0xbfb8aa3b, v50
	v_exp_f32_e32 v0, v0
	s_nop 0
	v_add_f32_e32 v0, 1.0, v0
	v_div_scale_f32 v50, s[0:1], v0, v0, 1.0
	v_rcp_f32_e32 v66, v50
	s_nop 0
	v_fma_f32 v67, -v50, v66, 1.0
	v_fmac_f32_e32 v66, v67, v66
	v_div_scale_f32 v67, vcc, 1.0, v0, 1.0
	v_mul_f32_e32 v68, v67, v66
	v_fma_f32 v69, -v50, v68, v67
	v_fmac_f32_e32 v68, v69, v66
	v_fma_f32 v50, -v50, v68, v67
	v_div_fmas_f32 v50, v50, v66, v68
	v_div_fixup_f32 v0, v50, v0, 1.0
	v_fma_f32 v0, v0, s80, 0.5
	v_cvt_u32_f32_e32 v116, v0
	v_mul_f32_e32 v0, 0xbfb8aa3b, v51
	v_exp_f32_e32 v0, v0
	s_nop 0
	v_add_f32_e32 v0, 1.0, v0
	v_div_scale_f32 v50, s[0:1], v0, v0, 1.0
	v_rcp_f32_e32 v51, v50
	s_nop 0
	v_fma_f32 v66, -v50, v51, 1.0
	v_fmac_f32_e32 v51, v66, v51
	v_div_scale_f32 v66, vcc, 1.0, v0, 1.0
	v_mul_f32_e32 v67, v66, v51
	v_fma_f32 v68, -v50, v67, v66
	v_fmac_f32_e32 v67, v68, v51
	v_fma_f32 v50, -v50, v67, v66
	v_div_fmas_f32 v50, v50, v51, v67
	v_div_fixup_f32 v0, v50, v0, 1.0
	v_mul_f32_e32 v50, 0xbfb8aa3b, v52
	v_exp_f32_e32 v50, v50
	v_fma_f32 v0, v0, s80, 0.5
	v_cvt_u32_f32_e32 v0, v0
	v_add_f32_e32 v50, 1.0, v50
	v_div_scale_f32 v51, s[0:1], v50, v50, 1.0
	v_rcp_f32_e32 v52, v51
	v_lshl_or_b32 v118, v0, 8, v116
	v_mul_f32_e32 v0, 0xbfb8aa3b, v54
	v_exp_f32_e32 v0, v0
	v_fma_f32 v66, -v51, v52, 1.0
	v_fmac_f32_e32 v52, v66, v52
	v_div_scale_f32 v66, vcc, 1.0, v50, 1.0
	v_mul_f32_e32 v67, v66, v52
	v_fma_f32 v68, -v51, v67, v66
	v_fmac_f32_e32 v67, v68, v52
	v_fma_f32 v51, -v51, v67, v66
	v_div_fmas_f32 v51, v51, v52, v67
	v_div_fixup_f32 v50, v51, v50, 1.0
	v_mul_f32_e32 v51, 0xbfb8aa3b, v53
	v_exp_f32_e32 v51, v51
	v_fma_f32 v50, v50, s80, 0.5
	v_cvt_u32_f32_sdwa v50, v50 dst_sel:WORD_1 dst_unused:UNUSED_PAD src0_sel:DWORD
	v_add_f32_e32 v0, 1.0, v0
	v_add_f32_e32 v51, 1.0, v51
	v_div_scale_f32 v52, s[0:1], v51, v51, 1.0
	v_rcp_f32_e32 v53, v52
	s_nop 0
	v_fma_f32 v66, -v52, v53, 1.0
	v_fmac_f32_e32 v53, v66, v53
	v_div_scale_f32 v66, vcc, 1.0, v51, 1.0
	v_mul_f32_e32 v67, v66, v53
	v_fma_f32 v68, -v52, v67, v66
	v_fmac_f32_e32 v67, v68, v53
	v_fma_f32 v52, -v52, v67, v66
	v_div_fmas_f32 v52, v52, v53, v67
	v_div_fixup_f32 v51, v52, v51, 1.0
	v_fma_f32 v51, v51, s80, 0.5
	v_cvt_u32_f32_sdwa v51, v51 dst_sel:BYTE_3 dst_unused:UNUSED_PAD src0_sel:DWORD
	s_nop 0
	v_or3_b32 v117, v50, v51, v118
	v_div_scale_f32 v50, s[0:1], v0, v0, 1.0
	v_rcp_f32_e32 v51, v50
	s_nop 0
	v_fma_f32 v52, -v50, v51, 1.0
	v_fmac_f32_e32 v51, v52, v51
	v_div_scale_f32 v52, vcc, 1.0, v0, 1.0
	v_mul_f32_e32 v53, v52, v51
	v_fma_f32 v54, -v50, v53, v52
	v_fmac_f32_e32 v53, v54, v51
	v_fma_f32 v50, -v50, v53, v52
	v_div_fmas_f32 v50, v50, v51, v53
	v_div_fixup_f32 v0, v50, v0, 1.0
	v_fma_f32 v0, v0, s80, 0.5
	v_cvt_u32_f32_e32 v119, v0
	v_mul_f32_e32 v0, 0xbfb8aa3b, v55
	v_exp_f32_e32 v0, v0
	s_nop 0
	v_add_f32_e32 v0, 1.0, v0
	v_div_scale_f32 v50, s[0:1], v0, v0, 1.0
	v_rcp_f32_e32 v51, v50
	s_nop 0
	v_fma_f32 v52, -v50, v51, 1.0
	v_fmac_f32_e32 v51, v52, v51
	v_div_scale_f32 v52, vcc, 1.0, v0, 1.0
	v_mul_f32_e32 v53, v52, v51
	v_fma_f32 v54, -v50, v53, v52
	v_fmac_f32_e32 v53, v54, v51
	v_fma_f32 v50, -v50, v53, v52
	v_div_fmas_f32 v50, v50, v51, v53
	v_div_fixup_f32 v0, v50, v0, 1.0
	v_mul_f32_e32 v50, 0xbfb8aa3b, v56
	v_exp_f32_e32 v50, v50
	v_fma_f32 v0, v0, s80, 0.5
	v_cvt_u32_f32_e32 v0, v0
	v_add_f32_e32 v50, 1.0, v50
	v_div_scale_f32 v51, s[0:1], v50, v50, 1.0
	v_rcp_f32_e32 v52, v51
	v_lshl_or_b32 v121, v0, 8, v119
	v_mul_f32_e32 v0, 0xbfb8aa3b, v58
	v_exp_f32_e32 v0, v0
	v_fma_f32 v53, -v51, v52, 1.0
	v_fmac_f32_e32 v52, v53, v52
	v_div_scale_f32 v53, vcc, 1.0, v50, 1.0
	v_mul_f32_e32 v54, v53, v52
	v_fma_f32 v55, -v51, v54, v53
	v_fmac_f32_e32 v54, v55, v52
	v_fma_f32 v51, -v51, v54, v53
	v_div_fmas_f32 v51, v51, v52, v54
	v_div_fixup_f32 v50, v51, v50, 1.0
	v_mul_f32_e32 v51, 0xbfb8aa3b, v57
	v_exp_f32_e32 v51, v51
	v_fma_f32 v50, v50, s80, 0.5
	v_cvt_u32_f32_sdwa v50, v50 dst_sel:WORD_1 dst_unused:UNUSED_PAD src0_sel:DWORD
	v_add_f32_e32 v0, 1.0, v0
	v_add_f32_e32 v51, 1.0, v51
	v_div_scale_f32 v52, s[0:1], v51, v51, 1.0
	v_rcp_f32_e32 v53, v52
	s_nop 0
	v_fma_f32 v54, -v52, v53, 1.0
	v_fmac_f32_e32 v53, v54, v53
	v_div_scale_f32 v54, vcc, 1.0, v51, 1.0
	v_mul_f32_e32 v55, v54, v53
	v_fma_f32 v56, -v52, v55, v54
	v_fmac_f32_e32 v55, v56, v53
	v_fma_f32 v52, -v52, v55, v54
	v_div_fmas_f32 v52, v52, v53, v55
	v_div_fixup_f32 v51, v52, v51, 1.0
	v_fma_f32 v51, v51, s80, 0.5
	v_cvt_u32_f32_sdwa v51, v51 dst_sel:BYTE_3 dst_unused:UNUSED_PAD src0_sel:DWORD
	s_nop 0
	v_or3_b32 v120, v50, v51, v121
	v_div_scale_f32 v50, s[0:1], v0, v0, 1.0
	v_rcp_f32_e32 v51, v50
	s_nop 0
	v_fma_f32 v52, -v50, v51, 1.0
	v_fmac_f32_e32 v51, v52, v51
	v_div_scale_f32 v52, vcc, 1.0, v0, 1.0
	v_mul_f32_e32 v53, v52, v51
	v_fma_f32 v54, -v50, v53, v52
	v_fmac_f32_e32 v53, v54, v51
	v_fma_f32 v50, -v50, v53, v52
	v_div_fmas_f32 v50, v50, v51, v53
	v_div_fixup_f32 v0, v50, v0, 1.0
	v_fma_f32 v0, v0, s80, 0.5
	v_cvt_u32_f32_e32 v122, v0
	v_mul_f32_e32 v0, 0xbfb8aa3b, v59
	v_exp_f32_e32 v0, v0
	s_nop 0
	v_add_f32_e32 v0, 1.0, v0
	v_div_scale_f32 v50, s[0:1], v0, v0, 1.0
	v_rcp_f32_e32 v51, v50
	s_nop 0
	v_fma_f32 v52, -v50, v51, 1.0
	v_fmac_f32_e32 v51, v52, v51
	v_div_scale_f32 v52, vcc, 1.0, v0, 1.0
	v_mul_f32_e32 v53, v52, v51
	v_fma_f32 v54, -v50, v53, v52
	v_fmac_f32_e32 v53, v54, v51
	v_fma_f32 v50, -v50, v53, v52
	v_div_fmas_f32 v50, v50, v51, v53
	v_div_fixup_f32 v0, v50, v0, 1.0
	v_mul_f32_e32 v50, 0xbfb8aa3b, v60
	v_exp_f32_e32 v50, v50
	v_fma_f32 v0, v0, s80, 0.5
	v_cvt_u32_f32_e32 v0, v0
	v_add_f32_e32 v50, 1.0, v50
	v_div_scale_f32 v51, s[0:1], v50, v50, 1.0
	v_rcp_f32_e32 v52, v51
	v_lshl_or_b32 v124, v0, 8, v122
	v_mul_f32_e32 v0, 0xbfb8aa3b, v62
	v_exp_f32_e32 v0, v0
	v_fma_f32 v53, -v51, v52, 1.0
	v_fmac_f32_e32 v52, v53, v52
	v_div_scale_f32 v53, vcc, 1.0, v50, 1.0
	v_mul_f32_e32 v54, v53, v52
	v_fma_f32 v55, -v51, v54, v53
	v_fmac_f32_e32 v54, v55, v52
	v_fma_f32 v51, -v51, v54, v53
	v_div_fmas_f32 v51, v51, v52, v54
	v_div_fixup_f32 v50, v51, v50, 1.0
	v_mul_f32_e32 v51, 0xbfb8aa3b, v61
	v_exp_f32_e32 v51, v51
	v_fma_f32 v50, v50, s80, 0.5
	v_cvt_u32_f32_sdwa v50, v50 dst_sel:WORD_1 dst_unused:UNUSED_PAD src0_sel:DWORD
	v_add_f32_e32 v0, 1.0, v0
	v_add_f32_e32 v51, 1.0, v51
	v_div_scale_f32 v52, s[0:1], v51, v51, 1.0
	v_rcp_f32_e32 v53, v52
	s_nop 0
	v_fma_f32 v54, -v52, v53, 1.0
	v_fmac_f32_e32 v53, v54, v53
	v_div_scale_f32 v54, vcc, 1.0, v51, 1.0
	v_mul_f32_e32 v55, v54, v53
	v_fma_f32 v56, -v52, v55, v54
	v_fmac_f32_e32 v55, v56, v53
	v_fma_f32 v52, -v52, v55, v54
	v_div_fmas_f32 v52, v52, v53, v55
	v_div_fixup_f32 v51, v52, v51, 1.0
	v_fma_f32 v51, v51, s80, 0.5
	v_cvt_u32_f32_sdwa v51, v51 dst_sel:BYTE_3 dst_unused:UNUSED_PAD src0_sel:DWORD
	s_nop 0
	v_or3_b32 v123, v50, v51, v124
	v_div_scale_f32 v50, s[0:1], v0, v0, 1.0
	v_rcp_f32_e32 v51, v50
	s_nop 0
	v_fma_f32 v52, -v50, v51, 1.0
	v_fmac_f32_e32 v51, v52, v51
	v_div_scale_f32 v52, vcc, 1.0, v0, 1.0
	v_mul_f32_e32 v53, v52, v51
	v_fma_f32 v54, -v50, v53, v52
	v_fmac_f32_e32 v53, v54, v51
	v_fma_f32 v50, -v50, v53, v52
	v_div_fmas_f32 v50, v50, v51, v53
	v_div_fixup_f32 v0, v50, v0, 1.0
	v_fma_f32 v0, v0, s80, 0.5
	v_cvt_u32_f32_e32 v125, v0
	v_mul_f32_e32 v0, 0xbfb8aa3b, v63
	v_exp_f32_e32 v0, v0
	s_nop 0
	v_add_f32_e32 v0, 1.0, v0
	v_div_scale_f32 v50, s[0:1], v0, v0, 1.0
	v_rcp_f32_e32 v51, v50
	s_nop 0
	v_fma_f32 v52, -v50, v51, 1.0
	v_fmac_f32_e32 v51, v52, v51
	v_div_scale_f32 v52, vcc, 1.0, v0, 1.0
	v_mul_f32_e32 v53, v52, v51
	v_fma_f32 v54, -v50, v53, v52
	v_fmac_f32_e32 v53, v54, v51
	v_fma_f32 v50, -v50, v53, v52
	v_div_fmas_f32 v50, v50, v51, v53
	v_div_fixup_f32 v0, v50, v0, 1.0
	v_mul_f32_e32 v50, 0xbfb8aa3b, v64
	v_exp_f32_e32 v50, v50
	v_fma_f32 v0, v0, s80, 0.5
	v_cvt_u32_f32_e32 v0, v0
	v_add_f32_e32 v50, 1.0, v50
	v_div_scale_f32 v51, s[0:1], v50, v50, 1.0
	v_rcp_f32_e32 v52, v51
	v_lshl_or_b32 v127, v0, 8, v125
	v_mul_f32_e32 v0, 0xbfb8aa3b, v34
	v_exp_f32_e32 v0, v0
	v_fma_f32 v53, -v51, v52, 1.0
	v_fmac_f32_e32 v52, v53, v52
	v_div_scale_f32 v53, vcc, 1.0, v50, 1.0
	v_mul_f32_e32 v54, v53, v52
	v_fma_f32 v55, -v51, v54, v53
	v_fmac_f32_e32 v54, v55, v52
	v_fma_f32 v51, -v51, v54, v53
	v_div_fmas_f32 v51, v51, v52, v54
	v_div_fixup_f32 v50, v51, v50, 1.0
	v_mul_f32_e32 v51, 0xbfb8aa3b, v65
	v_exp_f32_e32 v51, v51
	v_fma_f32 v50, v50, s80, 0.5
	v_cvt_u32_f32_sdwa v50, v50 dst_sel:WORD_1 dst_unused:UNUSED_PAD src0_sel:DWORD
	v_add_f32_e32 v0, 1.0, v0
	v_add_f32_e32 v51, 1.0, v51
	v_div_scale_f32 v52, s[0:1], v51, v51, 1.0
	v_rcp_f32_e32 v53, v52
	v_div_scale_f32 v34, s[0:1], v0, v0, 1.0
	v_fma_f32 v54, -v52, v53, 1.0
	v_fmac_f32_e32 v53, v54, v53
	v_div_scale_f32 v54, vcc, 1.0, v51, 1.0
	v_mul_f32_e32 v55, v54, v53
	v_fma_f32 v56, -v52, v55, v54
	v_fmac_f32_e32 v55, v56, v53
	v_fma_f32 v52, -v52, v55, v54
	v_div_fmas_f32 v52, v52, v53, v55
	v_div_fixup_f32 v51, v52, v51, 1.0
	v_fma_f32 v51, v51, s80, 0.5
	v_cvt_u32_f32_sdwa v51, v51 dst_sel:BYTE_3 dst_unused:UNUSED_PAD src0_sel:DWORD
	s_nop 0
	v_or3_b32 v126, v50, v51, v127
	v_rcp_f32_e32 v50, v34
	s_nop 0
	v_fma_f32 v51, -v34, v50, 1.0
	v_fmac_f32_e32 v50, v51, v50
	v_div_scale_f32 v51, vcc, 1.0, v0, 1.0
	v_mul_f32_e32 v52, v51, v50
	v_fma_f32 v53, -v34, v52, v51
	v_fmac_f32_e32 v52, v53, v50
	v_fma_f32 v34, -v34, v52, v51
	v_div_fmas_f32 v34, v34, v50, v52
	v_div_fixup_f32 v0, v34, v0, 1.0
	v_fma_f32 v0, v0, s80, 0.5
	v_cvt_u32_f32_e32 v128, v0
	v_mul_f32_e32 v0, 0xbfb8aa3b, v35
	v_exp_f32_e32 v0, v0
	s_nop 0
	v_add_f32_e32 v0, 1.0, v0
	v_div_scale_f32 v34, s[0:1], v0, v0, 1.0
	v_rcp_f32_e32 v35, v34
	s_nop 0
	v_fma_f32 v50, -v34, v35, 1.0
	v_fmac_f32_e32 v35, v50, v35
	v_div_scale_f32 v50, vcc, 1.0, v0, 1.0
	v_mul_f32_e32 v51, v50, v35
	v_fma_f32 v52, -v34, v51, v50
	v_fmac_f32_e32 v51, v52, v35
	v_fma_f32 v34, -v34, v51, v50
	v_div_fmas_f32 v34, v34, v35, v51
	v_div_fixup_f32 v0, v34, v0, 1.0
	v_mul_f32_e32 v34, 0xbfb8aa3b, v36
	v_exp_f32_e32 v34, v34
	v_fma_f32 v0, v0, s80, 0.5
	v_cvt_u32_f32_e32 v0, v0
	v_add_f32_e32 v34, 1.0, v34
	v_div_scale_f32 v35, s[0:1], v34, v34, 1.0
	v_rcp_f32_e32 v36, v35
	v_lshl_or_b32 v130, v0, 8, v128
	v_mul_f32_e32 v0, 0xbfb8aa3b, v38
	v_exp_f32_e32 v0, v0
	v_fma_f32 v50, -v35, v36, 1.0
	v_fmac_f32_e32 v36, v50, v36
	v_div_scale_f32 v50, vcc, 1.0, v34, 1.0
	v_mul_f32_e32 v51, v50, v36
	v_fma_f32 v52, -v35, v51, v50
	v_fmac_f32_e32 v51, v52, v36
	v_fma_f32 v35, -v35, v51, v50
	v_div_fmas_f32 v35, v35, v36, v51
	v_div_fixup_f32 v34, v35, v34, 1.0
	v_mul_f32_e32 v35, 0xbfb8aa3b, v37
	v_exp_f32_e32 v35, v35
	v_fma_f32 v34, v34, s80, 0.5
	v_cvt_u32_f32_sdwa v34, v34 dst_sel:WORD_1 dst_unused:UNUSED_PAD src0_sel:DWORD
	v_add_f32_e32 v0, 1.0, v0
	v_add_f32_e32 v35, 1.0, v35
	v_div_scale_f32 v36, s[0:1], v35, v35, 1.0
	v_rcp_f32_e32 v37, v36
	s_nop 0
	v_fma_f32 v50, -v36, v37, 1.0
	v_fmac_f32_e32 v37, v50, v37
	v_div_scale_f32 v50, vcc, 1.0, v35, 1.0
	v_mul_f32_e32 v51, v50, v37
	v_fma_f32 v52, -v36, v51, v50
	v_fmac_f32_e32 v51, v52, v37
	v_fma_f32 v36, -v36, v51, v50
	v_div_fmas_f32 v36, v36, v37, v51
	v_div_fixup_f32 v35, v36, v35, 1.0
	v_fma_f32 v35, v35, s80, 0.5
	v_cvt_u32_f32_sdwa v35, v35 dst_sel:BYTE_3 dst_unused:UNUSED_PAD src0_sel:DWORD
	s_nop 0
	v_or3_b32 v129, v34, v35, v130
	v_div_scale_f32 v34, s[0:1], v0, v0, 1.0
	v_rcp_f32_e32 v35, v34
	s_nop 0
	v_fma_f32 v36, -v34, v35, 1.0
	v_fmac_f32_e32 v35, v36, v35
	v_div_scale_f32 v36, vcc, 1.0, v0, 1.0
	v_mul_f32_e32 v37, v36, v35
	v_fma_f32 v38, -v34, v37, v36
	v_fmac_f32_e32 v37, v38, v35
	v_fma_f32 v34, -v34, v37, v36
	v_div_fmas_f32 v34, v34, v35, v37
	v_div_fixup_f32 v0, v34, v0, 1.0
	v_fma_f32 v0, v0, s80, 0.5
	v_cvt_u32_f32_e32 v131, v0
	v_mul_f32_e32 v0, 0xbfb8aa3b, v39
	v_exp_f32_e32 v0, v0
	s_nop 0
	v_add_f32_e32 v0, 1.0, v0
	v_div_scale_f32 v34, s[0:1], v0, v0, 1.0
	v_rcp_f32_e32 v35, v34
	s_nop 0
	v_fma_f32 v36, -v34, v35, 1.0
	v_fmac_f32_e32 v35, v36, v35
	v_div_scale_f32 v36, vcc, 1.0, v0, 1.0
	v_mul_f32_e32 v37, v36, v35
	v_fma_f32 v38, -v34, v37, v36
	v_fmac_f32_e32 v37, v38, v35
	v_fma_f32 v34, -v34, v37, v36
	v_div_fmas_f32 v34, v34, v35, v37
	v_div_fixup_f32 v0, v34, v0, 1.0
	v_mul_f32_e32 v34, 0xbfb8aa3b, v40
	v_exp_f32_e32 v34, v34
	v_fma_f32 v0, v0, s80, 0.5
	v_cvt_u32_f32_e32 v0, v0
	v_add_f32_e32 v34, 1.0, v34
	v_div_scale_f32 v35, s[0:1], v34, v34, 1.0
	v_rcp_f32_e32 v36, v35
	v_lshl_or_b32 v133, v0, 8, v131
	v_mul_f32_e32 v0, 0xbfb8aa3b, v42
	v_exp_f32_e32 v0, v0
	v_fma_f32 v37, -v35, v36, 1.0
	v_fmac_f32_e32 v36, v37, v36
	v_div_scale_f32 v37, vcc, 1.0, v34, 1.0
	v_mul_f32_e32 v38, v37, v36
	v_fma_f32 v39, -v35, v38, v37
	v_fmac_f32_e32 v38, v39, v36
	v_fma_f32 v35, -v35, v38, v37
	v_div_fmas_f32 v35, v35, v36, v38
	v_div_fixup_f32 v34, v35, v34, 1.0
	v_mul_f32_e32 v35, 0xbfb8aa3b, v41
	v_exp_f32_e32 v35, v35
	v_fma_f32 v34, v34, s80, 0.5
	v_cvt_u32_f32_sdwa v34, v34 dst_sel:WORD_1 dst_unused:UNUSED_PAD src0_sel:DWORD
	v_add_f32_e32 v0, 1.0, v0
	v_add_f32_e32 v35, 1.0, v35
	v_div_scale_f32 v36, s[0:1], v35, v35, 1.0
	v_rcp_f32_e32 v37, v36
	s_nop 0
	v_fma_f32 v38, -v36, v37, 1.0
	v_fmac_f32_e32 v37, v38, v37
	v_div_scale_f32 v38, vcc, 1.0, v35, 1.0
	v_mul_f32_e32 v39, v38, v37
	v_fma_f32 v40, -v36, v39, v38
	v_fmac_f32_e32 v39, v40, v37
	v_fma_f32 v36, -v36, v39, v38
	v_div_fmas_f32 v36, v36, v37, v39
	v_div_fixup_f32 v35, v36, v35, 1.0
	v_fma_f32 v35, v35, s80, 0.5
	v_cvt_u32_f32_sdwa v35, v35 dst_sel:BYTE_3 dst_unused:UNUSED_PAD src0_sel:DWORD
	s_nop 0
	v_or3_b32 v132, v34, v35, v133
	v_div_scale_f32 v34, s[0:1], v0, v0, 1.0
	v_rcp_f32_e32 v35, v34
	s_nop 0
	v_fma_f32 v36, -v34, v35, 1.0
	v_fmac_f32_e32 v35, v36, v35
	v_div_scale_f32 v36, vcc, 1.0, v0, 1.0
	v_mul_f32_e32 v37, v36, v35
	v_fma_f32 v38, -v34, v37, v36
	v_fmac_f32_e32 v37, v38, v35
	v_fma_f32 v34, -v34, v37, v36
	v_div_fmas_f32 v34, v34, v35, v37
	v_div_fixup_f32 v0, v34, v0, 1.0
	v_fma_f32 v0, v0, s80, 0.5
	v_cvt_u32_f32_e32 v134, v0
	v_mul_f32_e32 v0, 0xbfb8aa3b, v43
	v_exp_f32_e32 v0, v0
	s_nop 0
	v_add_f32_e32 v0, 1.0, v0
	v_div_scale_f32 v34, s[0:1], v0, v0, 1.0
	v_rcp_f32_e32 v35, v34
	s_nop 0
	v_fma_f32 v36, -v34, v35, 1.0
	v_fmac_f32_e32 v35, v36, v35
	v_div_scale_f32 v36, vcc, 1.0, v0, 1.0
	v_mul_f32_e32 v37, v36, v35
	v_fma_f32 v38, -v34, v37, v36
	v_fmac_f32_e32 v37, v38, v35
	v_fma_f32 v34, -v34, v37, v36
	v_div_fmas_f32 v34, v34, v35, v37
	v_div_fixup_f32 v0, v34, v0, 1.0
	v_mul_f32_e32 v34, 0xbfb8aa3b, v44
	v_exp_f32_e32 v34, v34
	v_fma_f32 v0, v0, s80, 0.5
	v_cvt_u32_f32_e32 v0, v0
	v_add_f32_e32 v34, 1.0, v34
	v_div_scale_f32 v35, s[0:1], v34, v34, 1.0
	v_rcp_f32_e32 v36, v35
	v_lshl_or_b32 v136, v0, 8, v134
	v_mul_f32_e32 v0, 0xbfb8aa3b, v46
	v_exp_f32_e32 v0, v0
	v_fma_f32 v37, -v35, v36, 1.0
	v_fmac_f32_e32 v36, v37, v36
	v_div_scale_f32 v37, vcc, 1.0, v34, 1.0
	v_mul_f32_e32 v38, v37, v36
	v_fma_f32 v39, -v35, v38, v37
	v_fmac_f32_e32 v38, v39, v36
	v_fma_f32 v35, -v35, v38, v37
	v_div_fmas_f32 v35, v35, v36, v38
	v_div_fixup_f32 v34, v35, v34, 1.0
	v_mul_f32_e32 v35, 0xbfb8aa3b, v45
	v_exp_f32_e32 v35, v35
	v_fma_f32 v34, v34, s80, 0.5
	v_cvt_u32_f32_sdwa v34, v34 dst_sel:WORD_1 dst_unused:UNUSED_PAD src0_sel:DWORD
	v_add_f32_e32 v0, 1.0, v0
	v_add_f32_e32 v35, 1.0, v35
	v_div_scale_f32 v36, s[0:1], v35, v35, 1.0
	v_rcp_f32_e32 v37, v36
	s_nop 0
	v_fma_f32 v38, -v36, v37, 1.0
	v_fmac_f32_e32 v37, v38, v37
	v_div_scale_f32 v38, vcc, 1.0, v35, 1.0
	v_mul_f32_e32 v39, v38, v37
	v_fma_f32 v40, -v36, v39, v38
	v_fmac_f32_e32 v39, v40, v37
	v_fma_f32 v36, -v36, v39, v38
	v_div_fmas_f32 v36, v36, v37, v39
	v_div_fixup_f32 v35, v36, v35, 1.0
	v_fma_f32 v35, v35, s80, 0.5
	v_cvt_u32_f32_sdwa v35, v35 dst_sel:BYTE_3 dst_unused:UNUSED_PAD src0_sel:DWORD
	s_nop 0
	v_or3_b32 v135, v34, v35, v136
	v_div_scale_f32 v34, s[0:1], v0, v0, 1.0
	v_rcp_f32_e32 v35, v34
	s_nop 0
	v_fma_f32 v36, -v34, v35, 1.0
	v_fmac_f32_e32 v35, v36, v35
	v_div_scale_f32 v36, vcc, 1.0, v0, 1.0
	v_mul_f32_e32 v37, v36, v35
	v_fma_f32 v38, -v34, v37, v36
	v_fmac_f32_e32 v37, v38, v35
	v_fma_f32 v34, -v34, v37, v36
	v_div_fmas_f32 v34, v34, v35, v37
	v_div_fixup_f32 v0, v34, v0, 1.0
	v_fma_f32 v0, v0, s80, 0.5
	v_cvt_u32_f32_e32 v137, v0
	v_mul_f32_e32 v0, 0xbfb8aa3b, v47
	v_exp_f32_e32 v0, v0
	s_nop 0
	v_add_f32_e32 v0, 1.0, v0
	v_div_scale_f32 v34, s[0:1], v0, v0, 1.0
	v_rcp_f32_e32 v35, v34
	s_nop 0
	v_fma_f32 v36, -v34, v35, 1.0
	v_fmac_f32_e32 v35, v36, v35
	v_div_scale_f32 v36, vcc, 1.0, v0, 1.0
	v_mul_f32_e32 v37, v36, v35
	v_fma_f32 v38, -v34, v37, v36
	v_fmac_f32_e32 v37, v38, v35
	v_fma_f32 v34, -v34, v37, v36
	v_div_fmas_f32 v34, v34, v35, v37
	v_div_fixup_f32 v0, v34, v0, 1.0
	v_mul_f32_e32 v34, 0xbfb8aa3b, v48
	v_exp_f32_e32 v34, v34
	v_fma_f32 v0, v0, s80, 0.5
	v_cvt_u32_f32_e32 v0, v0
	v_add_f32_e32 v34, 1.0, v34
	v_div_scale_f32 v35, s[0:1], v34, v34, 1.0
	v_rcp_f32_e32 v36, v35
	v_lshl_or_b32 v139, v0, 8, v137
	v_mul_f32_e32 v0, 0xbfb8aa3b, v18
	v_exp_f32_e32 v0, v0
	v_fma_f32 v37, -v35, v36, 1.0
	v_fmac_f32_e32 v36, v37, v36
	v_div_scale_f32 v37, vcc, 1.0, v34, 1.0
	v_mul_f32_e32 v38, v37, v36
	v_fma_f32 v39, -v35, v38, v37
	v_fmac_f32_e32 v38, v39, v36
	v_fma_f32 v35, -v35, v38, v37
	v_div_fmas_f32 v35, v35, v36, v38
	v_div_fixup_f32 v34, v35, v34, 1.0
	v_mul_f32_e32 v35, 0xbfb8aa3b, v49
	v_exp_f32_e32 v35, v35
	v_fma_f32 v34, v34, s80, 0.5
	v_cvt_u32_f32_sdwa v34, v34 dst_sel:WORD_1 dst_unused:UNUSED_PAD src0_sel:DWORD
	v_add_f32_e32 v0, 1.0, v0
	v_add_f32_e32 v35, 1.0, v35
	v_div_scale_f32 v36, s[0:1], v35, v35, 1.0
	v_rcp_f32_e32 v37, v36
	v_div_scale_f32 v18, s[0:1], v0, v0, 1.0
	v_fma_f32 v38, -v36, v37, 1.0
	v_fmac_f32_e32 v37, v38, v37
	v_div_scale_f32 v38, vcc, 1.0, v35, 1.0
	v_mul_f32_e32 v39, v38, v37
	v_fma_f32 v40, -v36, v39, v38
	v_fmac_f32_e32 v39, v40, v37
	v_fma_f32 v36, -v36, v39, v38
	v_div_fmas_f32 v36, v36, v37, v39
	v_div_fixup_f32 v35, v36, v35, 1.0
	v_fma_f32 v35, v35, s80, 0.5
	v_cvt_u32_f32_sdwa v35, v35 dst_sel:BYTE_3 dst_unused:UNUSED_PAD src0_sel:DWORD
	s_nop 0
	v_or3_b32 v138, v34, v35, v139
	v_rcp_f32_e32 v34, v18
	s_nop 0
	v_fma_f32 v35, -v18, v34, 1.0
	v_fmac_f32_e32 v34, v35, v34
	v_div_scale_f32 v35, vcc, 1.0, v0, 1.0
	v_mul_f32_e32 v36, v35, v34
	v_fma_f32 v37, -v18, v36, v35
	v_fmac_f32_e32 v36, v37, v34
	v_fma_f32 v18, -v18, v36, v35
	v_div_fmas_f32 v18, v18, v34, v36
	v_div_fixup_f32 v0, v18, v0, 1.0
	v_fma_f32 v0, v0, s80, 0.5
	v_cvt_u32_f32_e32 v140, v0
	v_mul_f32_e32 v0, 0xbfb8aa3b, v19
	v_exp_f32_e32 v0, v0
	s_nop 0
	v_add_f32_e32 v0, 1.0, v0
	v_div_scale_f32 v18, s[0:1], v0, v0, 1.0
	v_rcp_f32_e32 v19, v18
	s_nop 0
	v_fma_f32 v34, -v18, v19, 1.0
	v_fmac_f32_e32 v19, v34, v19
	v_div_scale_f32 v34, vcc, 1.0, v0, 1.0
	v_mul_f32_e32 v35, v34, v19
	v_fma_f32 v36, -v18, v35, v34
	v_fmac_f32_e32 v35, v36, v19
	v_fma_f32 v18, -v18, v35, v34
	v_div_fmas_f32 v18, v18, v19, v35
	v_div_fixup_f32 v0, v18, v0, 1.0
	v_mul_f32_e32 v18, 0xbfb8aa3b, v20
	v_exp_f32_e32 v18, v18
	v_fma_f32 v0, v0, s80, 0.5
	v_cvt_u32_f32_e32 v0, v0
	v_add_f32_e32 v18, 1.0, v18
	v_div_scale_f32 v19, s[0:1], v18, v18, 1.0
	v_rcp_f32_e32 v20, v19
	v_lshl_or_b32 v142, v0, 8, v140
	v_mul_f32_e32 v0, 0xbfb8aa3b, v22
	v_exp_f32_e32 v0, v0
	v_fma_f32 v34, -v19, v20, 1.0
	v_fmac_f32_e32 v20, v34, v20
	v_div_scale_f32 v34, vcc, 1.0, v18, 1.0
	v_mul_f32_e32 v35, v34, v20
	v_fma_f32 v36, -v19, v35, v34
	v_fmac_f32_e32 v35, v36, v20
	v_fma_f32 v19, -v19, v35, v34
	v_div_fmas_f32 v19, v19, v20, v35
	v_div_fixup_f32 v18, v19, v18, 1.0
	v_mul_f32_e32 v19, 0xbfb8aa3b, v21
	v_exp_f32_e32 v19, v19
	v_fma_f32 v18, v18, s80, 0.5
	v_cvt_u32_f32_sdwa v18, v18 dst_sel:WORD_1 dst_unused:UNUSED_PAD src0_sel:DWORD
	v_add_f32_e32 v0, 1.0, v0
	v_add_f32_e32 v19, 1.0, v19
	v_div_scale_f32 v20, s[0:1], v19, v19, 1.0
	v_rcp_f32_e32 v21, v20
	s_nop 0
	v_fma_f32 v34, -v20, v21, 1.0
	v_fmac_f32_e32 v21, v34, v21
	v_div_scale_f32 v34, vcc, 1.0, v19, 1.0
	v_mul_f32_e32 v35, v34, v21
	v_fma_f32 v36, -v20, v35, v34
	v_fmac_f32_e32 v35, v36, v21
	v_fma_f32 v20, -v20, v35, v34
	v_div_fmas_f32 v20, v20, v21, v35
	v_div_fixup_f32 v19, v20, v19, 1.0
	v_fma_f32 v19, v19, s80, 0.5
	v_cvt_u32_f32_sdwa v19, v19 dst_sel:BYTE_3 dst_unused:UNUSED_PAD src0_sel:DWORD
	s_nop 0
	v_or3_b32 v141, v18, v19, v142
	v_div_scale_f32 v18, s[0:1], v0, v0, 1.0
	v_rcp_f32_e32 v19, v18
	s_nop 0
	v_fma_f32 v20, -v18, v19, 1.0
	v_fmac_f32_e32 v19, v20, v19
	v_div_scale_f32 v20, vcc, 1.0, v0, 1.0
	v_mul_f32_e32 v21, v20, v19
	v_fma_f32 v22, -v18, v21, v20
	v_fmac_f32_e32 v21, v22, v19
	v_fma_f32 v18, -v18, v21, v20
	v_div_fmas_f32 v18, v18, v19, v21
	v_div_fixup_f32 v0, v18, v0, 1.0
	v_fma_f32 v0, v0, s80, 0.5
	v_cvt_u32_f32_e32 v143, v0
	v_mul_f32_e32 v0, 0xbfb8aa3b, v23
	v_exp_f32_e32 v0, v0
	s_nop 0
	v_add_f32_e32 v0, 1.0, v0
	v_div_scale_f32 v18, s[0:1], v0, v0, 1.0
	v_rcp_f32_e32 v19, v18
	s_nop 0
	v_fma_f32 v20, -v18, v19, 1.0
	v_fmac_f32_e32 v19, v20, v19
	v_div_scale_f32 v20, vcc, 1.0, v0, 1.0
	v_mul_f32_e32 v21, v20, v19
	v_fma_f32 v22, -v18, v21, v20
	v_fmac_f32_e32 v21, v22, v19
	v_fma_f32 v18, -v18, v21, v20
	v_div_fmas_f32 v18, v18, v19, v21
	v_div_fixup_f32 v0, v18, v0, 1.0
	v_mul_f32_e32 v18, 0xbfb8aa3b, v24
	v_exp_f32_e32 v18, v18
	v_fma_f32 v0, v0, s80, 0.5
	v_cvt_u32_f32_e32 v0, v0
	v_add_f32_e32 v18, 1.0, v18
	v_div_scale_f32 v19, s[0:1], v18, v18, 1.0
	v_rcp_f32_e32 v20, v19
	v_lshl_or_b32 v145, v0, 8, v143
	v_mul_f32_e32 v0, 0xbfb8aa3b, v26
	v_exp_f32_e32 v0, v0
	v_fma_f32 v21, -v19, v20, 1.0
	v_fmac_f32_e32 v20, v21, v20
	v_div_scale_f32 v21, vcc, 1.0, v18, 1.0
	v_mul_f32_e32 v22, v21, v20
	v_fma_f32 v23, -v19, v22, v21
	v_fmac_f32_e32 v22, v23, v20
	v_fma_f32 v19, -v19, v22, v21
	v_div_fmas_f32 v19, v19, v20, v22
	v_div_fixup_f32 v18, v19, v18, 1.0
	v_mul_f32_e32 v19, 0xbfb8aa3b, v25
	v_exp_f32_e32 v19, v19
	v_fma_f32 v18, v18, s80, 0.5
	v_cvt_u32_f32_sdwa v18, v18 dst_sel:WORD_1 dst_unused:UNUSED_PAD src0_sel:DWORD
	v_add_f32_e32 v0, 1.0, v0
	v_add_f32_e32 v19, 1.0, v19
	v_div_scale_f32 v20, s[0:1], v19, v19, 1.0
	v_rcp_f32_e32 v21, v20
	s_nop 0
	v_fma_f32 v22, -v20, v21, 1.0
	v_fmac_f32_e32 v21, v22, v21
	v_div_scale_f32 v22, vcc, 1.0, v19, 1.0
	v_mul_f32_e32 v23, v22, v21
	v_fma_f32 v24, -v20, v23, v22
	v_fmac_f32_e32 v23, v24, v21
	v_fma_f32 v20, -v20, v23, v22
	v_div_fmas_f32 v20, v20, v21, v23
	v_div_fixup_f32 v19, v20, v19, 1.0
	v_fma_f32 v19, v19, s80, 0.5
	v_cvt_u32_f32_sdwa v19, v19 dst_sel:BYTE_3 dst_unused:UNUSED_PAD src0_sel:DWORD
	s_nop 0
	v_or3_b32 v144, v18, v19, v145
	v_div_scale_f32 v18, s[0:1], v0, v0, 1.0
	v_rcp_f32_e32 v19, v18
	s_nop 0
	v_fma_f32 v20, -v18, v19, 1.0
	v_fmac_f32_e32 v19, v20, v19
	v_div_scale_f32 v20, vcc, 1.0, v0, 1.0
	v_mul_f32_e32 v21, v20, v19
	v_fma_f32 v22, -v18, v21, v20
	v_fmac_f32_e32 v21, v22, v19
	v_fma_f32 v18, -v18, v21, v20
	v_div_fmas_f32 v18, v18, v19, v21
	v_div_fixup_f32 v0, v18, v0, 1.0
	v_fma_f32 v0, v0, s80, 0.5
	v_cvt_u32_f32_e32 v146, v0
	v_mul_f32_e32 v0, 0xbfb8aa3b, v27
	v_exp_f32_e32 v0, v0
	s_nop 0
	v_add_f32_e32 v0, 1.0, v0
	v_div_scale_f32 v18, s[0:1], v0, v0, 1.0
	v_rcp_f32_e32 v19, v18
	s_nop 0
	v_fma_f32 v20, -v18, v19, 1.0
	v_fmac_f32_e32 v19, v20, v19
	v_div_scale_f32 v20, vcc, 1.0, v0, 1.0
	v_mul_f32_e32 v21, v20, v19
	v_fma_f32 v22, -v18, v21, v20
	v_fmac_f32_e32 v21, v22, v19
	v_fma_f32 v18, -v18, v21, v20
	v_div_fmas_f32 v18, v18, v19, v21
	v_div_fixup_f32 v0, v18, v0, 1.0
	v_mul_f32_e32 v18, 0xbfb8aa3b, v28
	v_exp_f32_e32 v18, v18
	v_fma_f32 v0, v0, s80, 0.5
	v_cvt_u32_f32_e32 v0, v0
	v_add_f32_e32 v18, 1.0, v18
	v_div_scale_f32 v19, s[0:1], v18, v18, 1.0
	v_rcp_f32_e32 v20, v19
	v_lshl_or_b32 v148, v0, 8, v146
	v_mul_f32_e32 v0, 0xbfb8aa3b, v30
	v_exp_f32_e32 v0, v0
	v_fma_f32 v21, -v19, v20, 1.0
	v_fmac_f32_e32 v20, v21, v20
	v_div_scale_f32 v21, vcc, 1.0, v18, 1.0
	v_mul_f32_e32 v22, v21, v20
	v_fma_f32 v23, -v19, v22, v21
	v_fmac_f32_e32 v22, v23, v20
	v_fma_f32 v19, -v19, v22, v21
	v_div_fmas_f32 v19, v19, v20, v22
	v_div_fixup_f32 v18, v19, v18, 1.0
	v_mul_f32_e32 v19, 0xbfb8aa3b, v29
	v_exp_f32_e32 v19, v19
	v_fma_f32 v18, v18, s80, 0.5
	v_cvt_u32_f32_sdwa v18, v18 dst_sel:WORD_1 dst_unused:UNUSED_PAD src0_sel:DWORD
	v_add_f32_e32 v0, 1.0, v0
	v_add_f32_e32 v19, 1.0, v19
	v_div_scale_f32 v20, s[0:1], v19, v19, 1.0
	v_rcp_f32_e32 v21, v20
	s_nop 0
	v_fma_f32 v22, -v20, v21, 1.0
	v_fmac_f32_e32 v21, v22, v21
	v_div_scale_f32 v22, vcc, 1.0, v19, 1.0
	v_mul_f32_e32 v23, v22, v21
	v_fma_f32 v24, -v20, v23, v22
	v_fmac_f32_e32 v23, v24, v21
	v_fma_f32 v20, -v20, v23, v22
	v_div_fmas_f32 v20, v20, v21, v23
	v_div_fixup_f32 v19, v20, v19, 1.0
	v_fma_f32 v19, v19, s80, 0.5
	v_cvt_u32_f32_sdwa v19, v19 dst_sel:BYTE_3 dst_unused:UNUSED_PAD src0_sel:DWORD
	s_nop 0
	v_or3_b32 v147, v18, v19, v148
	v_div_scale_f32 v18, s[0:1], v0, v0, 1.0
	v_rcp_f32_e32 v19, v18
	s_nop 0
	v_fma_f32 v20, -v18, v19, 1.0
	v_fmac_f32_e32 v19, v20, v19
	v_div_scale_f32 v20, vcc, 1.0, v0, 1.0
	v_mul_f32_e32 v21, v20, v19
	v_fma_f32 v22, -v18, v21, v20
	v_fmac_f32_e32 v21, v22, v19
	v_fma_f32 v18, -v18, v21, v20
	v_div_fmas_f32 v18, v18, v19, v21
	v_div_fixup_f32 v0, v18, v0, 1.0
	v_fma_f32 v0, v0, s80, 0.5
	v_cvt_u32_f32_e32 v149, v0
	v_mul_f32_e32 v0, 0xbfb8aa3b, v31
	v_exp_f32_e32 v0, v0
	s_nop 0
	v_add_f32_e32 v0, 1.0, v0
	v_div_scale_f32 v18, s[0:1], v0, v0, 1.0
	v_rcp_f32_e32 v19, v18
	s_nop 0
	v_fma_f32 v20, -v18, v19, 1.0
	v_fmac_f32_e32 v19, v20, v19
	v_div_scale_f32 v20, vcc, 1.0, v0, 1.0
	v_mul_f32_e32 v21, v20, v19
	v_fma_f32 v22, -v18, v21, v20
	v_fmac_f32_e32 v21, v22, v19
	v_fma_f32 v18, -v18, v21, v20
	v_div_fmas_f32 v18, v18, v19, v21
	v_div_fixup_f32 v0, v18, v0, 1.0
	v_mul_f32_e32 v18, 0xbfb8aa3b, v32
	v_exp_f32_e32 v18, v18
	v_fma_f32 v0, v0, s80, 0.5
	v_cvt_u32_f32_e32 v0, v0
	v_add_f32_e32 v18, 1.0, v18
	v_div_scale_f32 v19, s[0:1], v18, v18, 1.0
	v_rcp_f32_e32 v20, v19
	v_lshl_or_b32 v151, v0, 8, v149
	v_mul_f32_e32 v0, 0xbfb8aa3b, v2
	v_exp_f32_e32 v0, v0
	v_fma_f32 v21, -v19, v20, 1.0
	v_fmac_f32_e32 v20, v21, v20
	v_div_scale_f32 v21, vcc, 1.0, v18, 1.0
	v_mul_f32_e32 v22, v21, v20
	v_fma_f32 v23, -v19, v22, v21
	v_fmac_f32_e32 v22, v23, v20
	v_fma_f32 v19, -v19, v22, v21
	v_div_fmas_f32 v19, v19, v20, v22
	v_div_fixup_f32 v18, v19, v18, 1.0
	v_mul_f32_e32 v19, 0xbfb8aa3b, v33
	v_exp_f32_e32 v19, v19
	v_fma_f32 v18, v18, s80, 0.5
	v_cvt_u32_f32_sdwa v18, v18 dst_sel:WORD_1 dst_unused:UNUSED_PAD src0_sel:DWORD
	v_add_f32_e32 v0, 1.0, v0
	v_add_f32_e32 v19, 1.0, v19
	v_div_scale_f32 v20, s[0:1], v19, v19, 1.0
	v_rcp_f32_e32 v21, v20
	v_div_scale_f32 v2, s[0:1], v0, v0, 1.0
	v_fma_f32 v22, -v20, v21, 1.0
	v_fmac_f32_e32 v21, v22, v21
	v_div_scale_f32 v22, vcc, 1.0, v19, 1.0
	v_mul_f32_e32 v23, v22, v21
	v_fma_f32 v24, -v20, v23, v22
	v_fmac_f32_e32 v23, v24, v21
	v_fma_f32 v20, -v20, v23, v22
	v_div_fmas_f32 v20, v20, v21, v23
	v_div_fixup_f32 v19, v20, v19, 1.0
	v_fma_f32 v19, v19, s80, 0.5
	v_cvt_u32_f32_sdwa v19, v19 dst_sel:BYTE_3 dst_unused:UNUSED_PAD src0_sel:DWORD
	s_nop 0
	v_or3_b32 v150, v18, v19, v151
	v_rcp_f32_e32 v18, v2
	s_nop 0
	v_fma_f32 v19, -v2, v18, 1.0
	v_fmac_f32_e32 v18, v19, v18
	v_div_scale_f32 v19, vcc, 1.0, v0, 1.0
	v_mul_f32_e32 v20, v19, v18
	v_fma_f32 v21, -v2, v20, v19
	v_fmac_f32_e32 v20, v21, v18
	v_fma_f32 v2, -v2, v20, v19
	v_div_fmas_f32 v2, v2, v18, v20
	v_div_fixup_f32 v0, v2, v0, 1.0
	v_fma_f32 v0, v0, s80, 0.5
	v_cvt_u32_f32_e32 v152, v0
	v_mul_f32_e32 v0, 0xbfb8aa3b, v3
	v_exp_f32_e32 v0, v0
	s_nop 0
	v_add_f32_e32 v0, 1.0, v0
	v_div_scale_f32 v2, s[0:1], v0, v0, 1.0
	v_rcp_f32_e32 v3, v2
	s_nop 0
	v_fma_f32 v18, -v2, v3, 1.0
	v_fmac_f32_e32 v3, v18, v3
	v_div_scale_f32 v18, vcc, 1.0, v0, 1.0
	v_mul_f32_e32 v19, v18, v3
	v_fma_f32 v20, -v2, v19, v18
	v_fmac_f32_e32 v19, v20, v3
	v_fma_f32 v2, -v2, v19, v18
	v_div_fmas_f32 v2, v2, v3, v19
	v_div_fixup_f32 v0, v2, v0, 1.0
	v_mul_f32_e32 v2, 0xbfb8aa3b, v4
	v_exp_f32_e32 v2, v2
	v_fma_f32 v0, v0, s80, 0.5
	v_cvt_u32_f32_e32 v0, v0
	v_add_f32_e32 v2, 1.0, v2
	v_div_scale_f32 v3, s[0:1], v2, v2, 1.0
	v_rcp_f32_e32 v4, v3
	v_lshl_or_b32 v154, v0, 8, v152
	v_mul_f32_e32 v0, 0xbfb8aa3b, v6
	v_exp_f32_e32 v0, v0
	v_fma_f32 v18, -v3, v4, 1.0
	v_fmac_f32_e32 v4, v18, v4
	v_div_scale_f32 v18, vcc, 1.0, v2, 1.0
	v_mul_f32_e32 v19, v18, v4
	v_fma_f32 v20, -v3, v19, v18
	v_fmac_f32_e32 v19, v20, v4
	v_fma_f32 v3, -v3, v19, v18
	v_div_fmas_f32 v3, v3, v4, v19
	v_div_fixup_f32 v2, v3, v2, 1.0
	v_mul_f32_e32 v3, 0xbfb8aa3b, v5
	v_exp_f32_e32 v3, v3
	v_fma_f32 v2, v2, s80, 0.5
	v_cvt_u32_f32_sdwa v2, v2 dst_sel:WORD_1 dst_unused:UNUSED_PAD src0_sel:DWORD
	v_add_f32_e32 v0, 1.0, v0
	v_add_f32_e32 v3, 1.0, v3
	v_div_scale_f32 v4, s[0:1], v3, v3, 1.0
	v_rcp_f32_e32 v5, v4
	s_nop 0
	v_fma_f32 v18, -v4, v5, 1.0
	v_fmac_f32_e32 v5, v18, v5
	v_div_scale_f32 v18, vcc, 1.0, v3, 1.0
	v_mul_f32_e32 v19, v18, v5
	v_fma_f32 v20, -v4, v19, v18
	v_fmac_f32_e32 v19, v20, v5
	v_fma_f32 v4, -v4, v19, v18
	v_div_fmas_f32 v4, v4, v5, v19
	v_div_fixup_f32 v3, v4, v3, 1.0
	v_fma_f32 v3, v3, s80, 0.5
	v_cvt_u32_f32_sdwa v3, v3 dst_sel:BYTE_3 dst_unused:UNUSED_PAD src0_sel:DWORD
	s_nop 0
	v_or3_b32 v153, v2, v3, v154
	v_div_scale_f32 v2, s[0:1], v0, v0, 1.0
	v_rcp_f32_e32 v3, v2
	s_nop 0
	v_fma_f32 v4, -v2, v3, 1.0
	v_fmac_f32_e32 v3, v4, v3
	v_div_scale_f32 v4, vcc, 1.0, v0, 1.0
	v_mul_f32_e32 v5, v4, v3
	v_fma_f32 v6, -v2, v5, v4
	v_fmac_f32_e32 v5, v6, v3
	v_fma_f32 v2, -v2, v5, v4
	v_div_fmas_f32 v2, v2, v3, v5
	v_div_fixup_f32 v0, v2, v0, 1.0
	v_fma_f32 v0, v0, s80, 0.5
	v_cvt_u32_f32_e32 v155, v0
	v_mul_f32_e32 v0, 0xbfb8aa3b, v7
	v_exp_f32_e32 v0, v0
	s_nop 0
	v_add_f32_e32 v0, 1.0, v0
	v_div_scale_f32 v2, s[0:1], v0, v0, 1.0
	v_rcp_f32_e32 v3, v2
	s_nop 0
	v_fma_f32 v4, -v2, v3, 1.0
	v_fmac_f32_e32 v3, v4, v3
	v_div_scale_f32 v4, vcc, 1.0, v0, 1.0
	v_mul_f32_e32 v5, v4, v3
	v_fma_f32 v6, -v2, v5, v4
	v_fmac_f32_e32 v5, v6, v3
	v_fma_f32 v2, -v2, v5, v4
	v_div_fmas_f32 v2, v2, v3, v5
	v_div_fixup_f32 v0, v2, v0, 1.0
	v_mul_f32_e32 v2, 0xbfb8aa3b, v8
	v_exp_f32_e32 v2, v2
	v_fma_f32 v0, v0, s80, 0.5
	v_cvt_u32_f32_e32 v0, v0
	v_add_f32_e32 v2, 1.0, v2
	v_div_scale_f32 v3, s[0:1], v2, v2, 1.0
	v_rcp_f32_e32 v4, v3
	v_lshl_or_b32 v157, v0, 8, v155
	v_mul_f32_e32 v0, 0xbfb8aa3b, v10
	v_exp_f32_e32 v0, v0
	v_fma_f32 v5, -v3, v4, 1.0
	v_fmac_f32_e32 v4, v5, v4
	v_div_scale_f32 v5, vcc, 1.0, v2, 1.0
	v_mul_f32_e32 v6, v5, v4
	v_fma_f32 v7, -v3, v6, v5
	v_fmac_f32_e32 v6, v7, v4
	v_fma_f32 v3, -v3, v6, v5
	v_div_fmas_f32 v3, v3, v4, v6
	v_div_fixup_f32 v2, v3, v2, 1.0
	v_mul_f32_e32 v3, 0xbfb8aa3b, v9
	v_exp_f32_e32 v3, v3
	v_fma_f32 v2, v2, s80, 0.5
	v_cvt_u32_f32_sdwa v2, v2 dst_sel:WORD_1 dst_unused:UNUSED_PAD src0_sel:DWORD
	v_add_f32_e32 v0, 1.0, v0
	v_add_f32_e32 v3, 1.0, v3
	v_div_scale_f32 v4, s[0:1], v3, v3, 1.0
	v_rcp_f32_e32 v5, v4
	s_nop 0
	v_fma_f32 v6, -v4, v5, 1.0
	v_fmac_f32_e32 v5, v6, v5
	v_div_scale_f32 v6, vcc, 1.0, v3, 1.0
	v_mul_f32_e32 v7, v6, v5
	v_fma_f32 v8, -v4, v7, v6
	v_fmac_f32_e32 v7, v8, v5
	v_fma_f32 v4, -v4, v7, v6
	v_div_fmas_f32 v4, v4, v5, v7
	v_div_fixup_f32 v3, v4, v3, 1.0
	v_fma_f32 v3, v3, s80, 0.5
	v_cvt_u32_f32_sdwa v3, v3 dst_sel:BYTE_3 dst_unused:UNUSED_PAD src0_sel:DWORD
	s_nop 0
	v_or3_b32 v156, v2, v3, v157
	v_div_scale_f32 v2, s[0:1], v0, v0, 1.0
	v_rcp_f32_e32 v3, v2
	s_nop 0
	v_fma_f32 v4, -v2, v3, 1.0
	v_fmac_f32_e32 v3, v4, v3
	v_div_scale_f32 v4, vcc, 1.0, v0, 1.0
	v_mul_f32_e32 v5, v4, v3
	v_fma_f32 v6, -v2, v5, v4
	v_fmac_f32_e32 v5, v6, v3
	v_fma_f32 v2, -v2, v5, v4
	v_div_fmas_f32 v2, v2, v3, v5
	v_div_fixup_f32 v0, v2, v0, 1.0
	v_fma_f32 v0, v0, s80, 0.5
	v_cvt_u32_f32_e32 v158, v0
	v_mul_f32_e32 v0, 0xbfb8aa3b, v11
	v_exp_f32_e32 v0, v0
	s_nop 0
	v_add_f32_e32 v0, 1.0, v0
	v_div_scale_f32 v2, s[0:1], v0, v0, 1.0
	v_rcp_f32_e32 v3, v2
	s_nop 0
	v_fma_f32 v4, -v2, v3, 1.0
	v_fmac_f32_e32 v3, v4, v3
	v_div_scale_f32 v4, vcc, 1.0, v0, 1.0
	v_mul_f32_e32 v5, v4, v3
	v_fma_f32 v6, -v2, v5, v4
	v_fmac_f32_e32 v5, v6, v3
	v_fma_f32 v2, -v2, v5, v4
	v_div_fmas_f32 v2, v2, v3, v5
	v_div_fixup_f32 v0, v2, v0, 1.0
	v_mul_f32_e32 v2, 0xbfb8aa3b, v12
	v_exp_f32_e32 v2, v2
	v_fma_f32 v0, v0, s80, 0.5
	v_cvt_u32_f32_e32 v0, v0
	v_add_f32_e32 v2, 1.0, v2
	v_div_scale_f32 v3, s[0:1], v2, v2, 1.0
	v_rcp_f32_e32 v4, v3
	v_lshl_or_b32 v160, v0, 8, v158
	v_mul_f32_e32 v0, 0xbfb8aa3b, v14
	v_exp_f32_e32 v0, v0
	v_fma_f32 v5, -v3, v4, 1.0
	v_fmac_f32_e32 v4, v5, v4
	v_div_scale_f32 v5, vcc, 1.0, v2, 1.0
	v_mul_f32_e32 v6, v5, v4
	v_fma_f32 v7, -v3, v6, v5
	v_fmac_f32_e32 v6, v7, v4
	v_fma_f32 v3, -v3, v6, v5
	v_div_fmas_f32 v3, v3, v4, v6
	v_div_fixup_f32 v2, v3, v2, 1.0
	v_mul_f32_e32 v3, 0xbfb8aa3b, v13
	v_exp_f32_e32 v3, v3
	v_fma_f32 v2, v2, s80, 0.5
	v_cvt_u32_f32_sdwa v2, v2 dst_sel:WORD_1 dst_unused:UNUSED_PAD src0_sel:DWORD
	v_add_f32_e32 v0, 1.0, v0
	v_add_f32_e32 v3, 1.0, v3
	v_div_scale_f32 v4, s[0:1], v3, v3, 1.0
	v_rcp_f32_e32 v5, v4
	s_nop 0
	v_fma_f32 v6, -v4, v5, 1.0
	v_fmac_f32_e32 v5, v6, v5
	v_div_scale_f32 v6, vcc, 1.0, v3, 1.0
	v_mul_f32_e32 v7, v6, v5
	v_fma_f32 v8, -v4, v7, v6
	v_fmac_f32_e32 v7, v8, v5
	v_fma_f32 v4, -v4, v7, v6
	v_div_fmas_f32 v4, v4, v5, v7
	v_div_fixup_f32 v3, v4, v3, 1.0
	v_fma_f32 v3, v3, s80, 0.5
	v_cvt_u32_f32_sdwa v3, v3 dst_sel:BYTE_3 dst_unused:UNUSED_PAD src0_sel:DWORD
	s_nop 0
	v_or3_b32 v159, v2, v3, v160
	v_div_scale_f32 v2, s[0:1], v0, v0, 1.0
	v_rcp_f32_e32 v3, v2
	s_nop 0
	v_fma_f32 v4, -v2, v3, 1.0
	v_fmac_f32_e32 v3, v4, v3
	v_div_scale_f32 v4, vcc, 1.0, v0, 1.0
	v_mul_f32_e32 v5, v4, v3
	v_fma_f32 v6, -v2, v5, v4
	v_fmac_f32_e32 v5, v6, v3
	v_fma_f32 v2, -v2, v5, v4
	v_div_fmas_f32 v2, v2, v3, v5
	v_div_fixup_f32 v0, v2, v0, 1.0
	v_fma_f32 v0, v0, s80, 0.5
	v_cvt_u32_f32_e32 v161, v0
	v_mul_f32_e32 v0, 0xbfb8aa3b, v15
	v_exp_f32_e32 v0, v0
	s_nop 0
	v_add_f32_e32 v0, 1.0, v0
	v_div_scale_f32 v2, s[0:1], v0, v0, 1.0
	v_rcp_f32_e32 v3, v2
	s_nop 0
	v_fma_f32 v4, -v2, v3, 1.0
	v_fmac_f32_e32 v3, v4, v3
	v_div_scale_f32 v4, vcc, 1.0, v0, 1.0
	v_mul_f32_e32 v5, v4, v3
	v_fma_f32 v6, -v2, v5, v4
	v_fmac_f32_e32 v5, v6, v3
	v_fma_f32 v2, -v2, v5, v4
	v_div_fmas_f32 v2, v2, v3, v5
	v_div_fixup_f32 v0, v2, v0, 1.0
	v_mul_f32_e32 v2, 0xbfb8aa3b, v16
	v_exp_f32_e32 v2, v2
	v_fma_f32 v0, v0, s80, 0.5
	v_cvt_u32_f32_e32 v0, v0
	v_add_f32_e32 v2, 1.0, v2
	v_div_scale_f32 v3, s[0:1], v2, v2, 1.0
	v_rcp_f32_e32 v4, v3
	v_lshl_or_b32 v163, v0, 8, v161
	v_fma_f32 v5, -v3, v4, 1.0
	v_fmac_f32_e32 v4, v5, v4
	v_div_scale_f32 v5, vcc, 1.0, v2, 1.0
	v_mul_f32_e32 v6, v5, v4
	v_fma_f32 v7, -v3, v6, v5
	v_fmac_f32_e32 v6, v7, v4
	v_fma_f32 v3, -v3, v6, v5
	v_div_fmas_f32 v3, v3, v4, v6
	v_div_fixup_f32 v2, v3, v2, 1.0
	v_mul_f32_e32 v3, 0xbfb8aa3b, v17
	v_exp_f32_e32 v3, v3
	v_fma_f32 v2, v2, s80, 0.5
	v_cvt_u32_f32_sdwa v2, v2 dst_sel:WORD_1 dst_unused:UNUSED_PAD src0_sel:DWORD
	v_add_f32_e32 v3, 1.0, v3
	v_div_scale_f32 v4, s[0:1], v3, v3, 1.0
	v_rcp_f32_e32 v5, v4
	s_movk_i32 s0, 0xaa0
	s_cselect_b32 s12, s0, 0x12a0
	s_mov_b32 s0, 0x12f0000
	v_fma_f32 v6, -v4, v5, 1.0
	v_fmac_f32_e32 v5, v6, v5
	v_div_scale_f32 v6, vcc, 1.0, v3, 1.0
	v_mul_f32_e32 v7, v6, v5
	v_fma_f32 v8, -v4, v7, v6
	v_fmac_f32_e32 v7, v8, v5
	v_fma_f32 v4, -v4, v7, v6
	v_div_fmas_f32 v4, v4, v5, v7
	s_cselect_b32 s13, s0, 0x13f0000
	s_cmp_eq_u32 s45, 0
	v_div_fixup_f32 v3, v4, v3, 1.0
	s_cselect_b64 vcc, -1, 0
	v_fma_f32 v3, v3, s80, 0.5
	s_and_b64 s[0:1], vcc, exec
	v_cvt_u32_f32_sdwa v3, v3 dst_sel:BYTE_3 dst_unused:UNUSED_PAD src0_sel:DWORD
	s_cselect_b32 s0, 0x2a0, s12
	s_cselect_b32 s13, 0x11f0000, s13
	s_lshl_b32 s0, s0, 1
	s_add_u32 s0, s43, s0
	v_mov_b32_e32 v6, v178
	s_addc_u32 s1, s44, 0
	v_or3_b32 v162, v2, v3, v163
	v_lshlrev_b32_e32 v0, 3, v6
	v_ashrrev_i32_e32 v2, 3, v6
	v_and_b32_e32 v36, 56, v0
	v_mov_b64_e32 v[4:5], s[0:1]
	s_add_u32 s12, s25, s13
	v_ashrrev_i32_e32 v3, 31, v2
	v_mad_i64_i32 v[4:5], s[0:1], v2, s77, v[4:5]
	v_lshlrev_b32_e32 v0, 1, v36
	s_addc_u32 s13, s42, 0
	v_lshl_add_u64 v[102:103], v[4:5], 0, v[0:1]
	v_lshlrev_b64 v[4:5], 10, v[2:3]
	v_lshl_add_u64 v[4:5], s[12:13], 0, v[4:5]
	v_and_b32_e32 v7, 31, v6
	v_lshl_add_u64 v[100:101], v[4:5], 0, v[0:1]
	v_lshrrev_b32_e32 v0, 1, v6
	v_and_or_b32 v3, v0, s35, v7
	v_and_b32_e32 v0, 16, v0
	v_mad_u64_u32 v[98:99], s[0:1], v3, s72, v[0:1]
	v_and_b32_e32 v0, 7, v178
	v_bfe_u32 v98, v178, 4, 3
	v_xor_b32_e32 v98, v98, v0
	v_sub_u32_e32 v98, v98, v0
	v_lshlrev_b32_e32 v98, 4, v98
	v_ashrrev_i32_e32 v99, 31, v98
	v_lshl_add_u64 v[102:103], v[102:103], 0, v[98:99]
	v_lshl_add_u64 v[100:101], v[100:101], 0, v[98:99]
	s_mov_b32 s15, 0x18000
	v_add_co_u32_e64 v104, s[0:1], s97, v102
	s_nop 1
	v_addc_co_u32_e64 v105, s[0:1], 0, v103, s[0:1]
	v_add_co_u32_e64 v106, s[0:1], s31, v100
	s_nop 1
	v_addc_co_u32_e64 v107, s[0:1], 0, v101, s[0:1]
	v_add_co_u32_e64 v108, s[0:1], s26, v102
	s_nop 1
	v_addc_co_u32_e64 v109, s[0:1], 0, v103, s[0:1]
	v_add_co_u32_e64 v110, s[0:1], s73, v100
	s_nop 1
	v_addc_co_u32_e64 v111, s[0:1], 0, v101, s[0:1]
	v_add_co_u32_e64 v112, s[0:1], s96, v102
	s_nop 1
	v_addc_co_u32_e64 v113, s[0:1], 0, v103, s[0:1]
	v_add_co_u32_e64 v114, s[0:1], s15, v100
	s_nop 1
	v_addc_co_u32_e64 v115, s[0:1], 0, v101, s[0:1]
	v_and_b32_e32 v0, 31, v178
	v_bfe_u32 v98, v178, 5, 1
	v_bfe_u32 v99, v178, 1, 3
	v_xor_b32_e32 v98, v98, v99
	v_lshlrev_b32_e32 v98, 4, v98
	v_lshl_add_u32 v98, v0, 7, v98
	v_bfe_u32 v99, v178, 7, 1
	v_lshl_add_u32 v222, v99, 13, v98
	v_bfe_u32 v99, v178, 6, 1
	v_lshl_add_u32 v226, v99, 13, v98
	v_add_u32_e32 v226, 0x4000, v226
	v_xor_b32_e32 v223, 32, v222
	v_xor_b32_e32 v227, 32, v226
	v_xor_b32_e32 v224, 64, v222
	v_xor_b32_e32 v228, 64, v226
	v_xor_b32_e32 v225, 96, v222
	v_xor_b32_e32 v229, 96, v226
	v_lshrrev_b32_e32 v98, 6, v178
	v_lshlrev_b32_e32 v98, 10, v98
	s_nop 1
	v_readfirstlane_b32 s14, v98
	s_waitcnt vmcnt(8)
	s_barrier
	ds_read_b128 v[66:69], v222 offset:2048
	ds_read_b128 v[70:73], v222 offset:6144
	ds_read_b128 v[74:77], v226 offset:2048
	ds_read_b128 v[78:81], v226 offset:6144
	ds_read_b128 v[82:85], v223 offset:2048
	ds_read_b128 v[86:89], v223 offset:6144
	ds_read_b128 v[90:93], v227 offset:2048
	ds_read_b128 v[94:97], v227 offset:6144
	ds_read_b128 v[230:233], v224 offset:2048
	ds_read_b128 v[234:237], v224 offset:6144
	ds_read_b128 v[238:241], v228 offset:2048
	ds_read_b128 v[242:245], v228 offset:6144
	s_waitcnt lgkmcnt(8)
	v_mfma_f32_32x32x16_bf16 v[2:17], v[66:69], v[74:77], 0
	v_mfma_f32_32x32x16_bf16 v[50:65], v[66:69], v[78:81], 0
	v_mfma_f32_32x32x16_bf16 v[34:49], v[70:73], v[74:77], 0
	v_mfma_f32_32x32x16_bf16 v[18:33], v[70:73], v[78:81], 0
	ds_read_b128 v[66:69], v225 offset:2048
	ds_read_b128 v[70:73], v225 offset:6144
	ds_read_b128 v[74:77], v229 offset:2048
	ds_read_b128 v[78:81], v229 offset:6144
	s_waitcnt lgkmcnt(8)
	v_mfma_f32_32x32x16_bf16 v[2:17], v[82:85], v[90:93], v[2:17]
	v_mfma_f32_32x32x16_bf16 v[50:65], v[82:85], v[94:97], v[50:65]
	v_mfma_f32_32x32x16_bf16 v[34:49], v[86:89], v[90:93], v[34:49]
	v_mfma_f32_32x32x16_bf16 v[18:33], v[86:89], v[94:97], v[18:33]
	s_waitcnt lgkmcnt(0)
	s_barrier
	s_add_u32 m0, s14, 0x700
	s_nop 0
	global_load_lds_dwordx4 v[102:103], off offset:256
	s_add_u32 m0, s14, 0x1700
	s_nop 0
	global_load_lds_dwordx4 v[104:105], off offset:256
	s_add_u32 m0, s14, 0x2700
	s_nop 0
	global_load_lds_dwordx4 v[108:109], off offset:256
	s_add_u32 m0, s14, 0x3700
	s_nop 0
	global_load_lds_dwordx4 v[112:113], off offset:256
	s_add_u32 m0, s14, 0x4700
	s_nop 0
	global_load_lds_dwordx4 v[100:101], off offset:256
	s_add_u32 m0, s14, 0x5700
	s_nop 0
	global_load_lds_dwordx4 v[106:107], off offset:256
	s_add_u32 m0, s14, 0x6700
	s_nop 0
	global_load_lds_dwordx4 v[110:111], off offset:256
	s_add_u32 m0, s14, 0x7700
	s_nop 0
	global_load_lds_dwordx4 v[114:115], off offset:256
	s_waitcnt vmcnt(8)
	s_barrier
	ds_read_b128 v[82:85], v222 offset:34816
	ds_read_b128 v[86:89], v222 offset:38912
	ds_read_b128 v[90:93], v226 offset:34816
	ds_read_b128 v[94:97], v226 offset:38912
	v_mfma_f32_32x32x16_bf16 v[2:17], v[230:233], v[238:241], v[2:17]
	v_mfma_f32_32x32x16_bf16 v[50:65], v[230:233], v[242:245], v[50:65]
	v_mfma_f32_32x32x16_bf16 v[34:49], v[234:237], v[238:241], v[34:49]
	v_mfma_f32_32x32x16_bf16 v[18:33], v[234:237], v[242:245], v[18:33]
	ds_read_b128 v[230:233], v223 offset:34816
	ds_read_b128 v[234:237], v223 offset:38912
	ds_read_b128 v[238:241], v227 offset:34816
	ds_read_b128 v[242:245], v227 offset:38912
	v_mfma_f32_32x32x16_bf16 v[2:17], v[66:69], v[74:77], v[2:17]
	v_mfma_f32_32x32x16_bf16 v[50:65], v[66:69], v[78:81], v[50:65]
	v_mfma_f32_32x32x16_bf16 v[34:49], v[70:73], v[74:77], v[34:49]
	v_mfma_f32_32x32x16_bf16 v[18:33], v[70:73], v[78:81], v[18:33]
	ds_read_b128 v[66:69], v224 offset:34816
	ds_read_b128 v[70:73], v224 offset:38912
	ds_read_b128 v[74:77], v228 offset:34816
	ds_read_b128 v[78:81], v228 offset:38912
	s_waitcnt lgkmcnt(8)
	v_mfma_f32_32x32x16_bf16 v[2:17], v[82:85], v[90:93], v[2:17]
	v_mfma_f32_32x32x16_bf16 v[50:65], v[82:85], v[94:97], v[50:65]
	v_mfma_f32_32x32x16_bf16 v[34:49], v[86:89], v[90:93], v[34:49]
	v_mfma_f32_32x32x16_bf16 v[18:33], v[86:89], v[94:97], v[18:33]
	ds_read_b128 v[82:85], v225 offset:34816
	ds_read_b128 v[86:89], v225 offset:38912
	ds_read_b128 v[90:93], v229 offset:34816
	ds_read_b128 v[94:97], v229 offset:38912
	s_waitcnt lgkmcnt(8)
	v_mfma_f32_32x32x16_bf16 v[2:17], v[230:233], v[238:241], v[2:17]
	v_mfma_f32_32x32x16_bf16 v[50:65], v[230:233], v[242:245], v[50:65]
	v_mfma_f32_32x32x16_bf16 v[34:49], v[234:237], v[238:241], v[34:49]
	v_mfma_f32_32x32x16_bf16 v[18:33], v[234:237], v[242:245], v[18:33]
	s_waitcnt lgkmcnt(0)
	s_barrier
	s_add_u32 m0, s14, 0x8680
	s_nop 0
	global_load_lds_dwordx4 v[102:103], off offset:384
	s_add_u32 m0, s14, 0x9680
	s_nop 0
	global_load_lds_dwordx4 v[104:105], off offset:384
	s_add_u32 m0, s14, 0xa680
	s_nop 0
	global_load_lds_dwordx4 v[108:109], off offset:384
	s_add_u32 m0, s14, 0xb680
	s_nop 0
	global_load_lds_dwordx4 v[112:113], off offset:384
	s_add_u32 m0, s14, 0xc680
	s_nop 0
	global_load_lds_dwordx4 v[100:101], off offset:384
	s_add_u32 m0, s14, 0xd680
	s_nop 0
	global_load_lds_dwordx4 v[106:107], off offset:384
	s_add_u32 m0, s14, 0xe680
	s_nop 0
	global_load_lds_dwordx4 v[110:111], off offset:384
	s_add_u32 m0, s14, 0xf680
	s_nop 0
	global_load_lds_dwordx4 v[114:115], off offset:384
	s_waitcnt vmcnt(8)
	s_barrier
	ds_read_b128 v[230:233], v222 offset:2048
	ds_read_b128 v[234:237], v222 offset:6144
	ds_read_b128 v[238:241], v226 offset:2048
	ds_read_b128 v[242:245], v226 offset:6144
	v_mfma_f32_32x32x16_bf16 v[2:17], v[66:69], v[74:77], v[2:17]
	v_mfma_f32_32x32x16_bf16 v[50:65], v[66:69], v[78:81], v[50:65]
	v_mfma_f32_32x32x16_bf16 v[34:49], v[70:73], v[74:77], v[34:49]
	v_mfma_f32_32x32x16_bf16 v[18:33], v[70:73], v[78:81], v[18:33]
	ds_read_b128 v[66:69], v223 offset:2048
	ds_read_b128 v[70:73], v223 offset:6144
	ds_read_b128 v[74:77], v227 offset:2048
	ds_read_b128 v[78:81], v227 offset:6144
	v_mfma_f32_32x32x16_bf16 v[2:17], v[82:85], v[90:93], v[2:17]
	v_mfma_f32_32x32x16_bf16 v[50:65], v[82:85], v[94:97], v[50:65]
	v_mfma_f32_32x32x16_bf16 v[34:49], v[86:89], v[90:93], v[34:49]
	v_mfma_f32_32x32x16_bf16 v[18:33], v[86:89], v[94:97], v[18:33]
	ds_read_b128 v[82:85], v224 offset:2048
	ds_read_b128 v[86:89], v224 offset:6144
	ds_read_b128 v[90:93], v228 offset:2048
	ds_read_b128 v[94:97], v228 offset:6144
	s_waitcnt lgkmcnt(8)
	v_mfma_f32_32x32x16_bf16 v[2:17], v[230:233], v[238:241], v[2:17]
	v_mfma_f32_32x32x16_bf16 v[50:65], v[230:233], v[242:245], v[50:65]
	v_mfma_f32_32x32x16_bf16 v[34:49], v[234:237], v[238:241], v[34:49]
	v_mfma_f32_32x32x16_bf16 v[18:33], v[234:237], v[242:245], v[18:33]
	ds_read_b128 v[230:233], v225 offset:2048
	ds_read_b128 v[234:237], v225 offset:6144
	ds_read_b128 v[238:241], v229 offset:2048
	ds_read_b128 v[242:245], v229 offset:6144
	s_waitcnt lgkmcnt(8)
	v_mfma_f32_32x32x16_bf16 v[2:17], v[66:69], v[74:77], v[2:17]
	v_mfma_f32_32x32x16_bf16 v[50:65], v[66:69], v[78:81], v[50:65]
	v_mfma_f32_32x32x16_bf16 v[34:49], v[70:73], v[74:77], v[34:49]
	v_mfma_f32_32x32x16_bf16 v[18:33], v[70:73], v[78:81], v[18:33]
	s_waitcnt lgkmcnt(0)
	s_barrier
	s_add_u32 m0, s14, 0x600
	s_nop 0
	global_load_lds_dwordx4 v[102:103], off offset:512
	s_add_u32 m0, s14, 0x1600
	s_nop 0
	global_load_lds_dwordx4 v[104:105], off offset:512
	s_add_u32 m0, s14, 0x2600
	s_nop 0
	global_load_lds_dwordx4 v[108:109], off offset:512
	s_add_u32 m0, s14, 0x3600
	s_nop 0
	global_load_lds_dwordx4 v[112:113], off offset:512
	s_add_u32 m0, s14, 0x4600
	s_nop 0
	global_load_lds_dwordx4 v[100:101], off offset:512
	s_add_u32 m0, s14, 0x5600
	s_nop 0
	global_load_lds_dwordx4 v[106:107], off offset:512
	s_add_u32 m0, s14, 0x6600
	s_nop 0
	global_load_lds_dwordx4 v[110:111], off offset:512
	s_add_u32 m0, s14, 0x7600
	s_nop 0
	global_load_lds_dwordx4 v[114:115], off offset:512
	s_waitcnt vmcnt(8)
	s_barrier
	ds_read_b128 v[66:69], v222 offset:34816
	ds_read_b128 v[70:73], v222 offset:38912
	ds_read_b128 v[74:77], v226 offset:34816
	ds_read_b128 v[78:81], v226 offset:38912
	v_mfma_f32_32x32x16_bf16 v[2:17], v[82:85], v[90:93], v[2:17]
	v_mfma_f32_32x32x16_bf16 v[50:65], v[82:85], v[94:97], v[50:65]
	v_mfma_f32_32x32x16_bf16 v[34:49], v[86:89], v[90:93], v[34:49]
	v_mfma_f32_32x32x16_bf16 v[18:33], v[86:89], v[94:97], v[18:33]
	ds_read_b128 v[82:85], v223 offset:34816
	ds_read_b128 v[86:89], v223 offset:38912
	ds_read_b128 v[90:93], v227 offset:34816
	ds_read_b128 v[94:97], v227 offset:38912
	v_mfma_f32_32x32x16_bf16 v[2:17], v[230:233], v[238:241], v[2:17]
	v_mfma_f32_32x32x16_bf16 v[50:65], v[230:233], v[242:245], v[50:65]
	v_mfma_f32_32x32x16_bf16 v[34:49], v[234:237], v[238:241], v[34:49]
	v_mfma_f32_32x32x16_bf16 v[18:33], v[234:237], v[242:245], v[18:33]
	ds_read_b128 v[230:233], v224 offset:34816
	ds_read_b128 v[234:237], v224 offset:38912
	ds_read_b128 v[238:241], v228 offset:34816
	ds_read_b128 v[242:245], v228 offset:38912
	s_waitcnt lgkmcnt(8)
	v_mfma_f32_32x32x16_bf16 v[2:17], v[66:69], v[74:77], v[2:17]
	v_mfma_f32_32x32x16_bf16 v[50:65], v[66:69], v[78:81], v[50:65]
	v_mfma_f32_32x32x16_bf16 v[34:49], v[70:73], v[74:77], v[34:49]
	v_mfma_f32_32x32x16_bf16 v[18:33], v[70:73], v[78:81], v[18:33]
	ds_read_b128 v[66:69], v225 offset:34816
	ds_read_b128 v[70:73], v225 offset:38912
	ds_read_b128 v[74:77], v229 offset:34816
	ds_read_b128 v[78:81], v229 offset:38912
	s_waitcnt lgkmcnt(8)
	v_mfma_f32_32x32x16_bf16 v[2:17], v[82:85], v[90:93], v[2:17]
	v_mfma_f32_32x32x16_bf16 v[50:65], v[82:85], v[94:97], v[50:65]
	v_mfma_f32_32x32x16_bf16 v[34:49], v[86:89], v[90:93], v[34:49]
	v_mfma_f32_32x32x16_bf16 v[18:33], v[86:89], v[94:97], v[18:33]
	s_waitcnt lgkmcnt(0)
	s_barrier
	s_add_u32 m0, s14, 0x8580
	s_nop 0
	global_load_lds_dwordx4 v[102:103], off offset:640
	s_add_u32 m0, s14, 0x9580
	s_nop 0
	global_load_lds_dwordx4 v[104:105], off offset:640
	s_add_u32 m0, s14, 0xa580
	s_nop 0
	global_load_lds_dwordx4 v[108:109], off offset:640
	s_add_u32 m0, s14, 0xb580
	s_nop 0
	global_load_lds_dwordx4 v[112:113], off offset:640
	s_add_u32 m0, s14, 0xc580
	s_nop 0
	global_load_lds_dwordx4 v[100:101], off offset:640
	s_add_u32 m0, s14, 0xd580
	s_nop 0
	global_load_lds_dwordx4 v[106:107], off offset:640
	s_add_u32 m0, s14, 0xe580
	s_nop 0
	global_load_lds_dwordx4 v[110:111], off offset:640
	s_add_u32 m0, s14, 0xf580
	s_nop 0
	global_load_lds_dwordx4 v[114:115], off offset:640
	s_waitcnt vmcnt(8)
	s_barrier
	ds_read_b128 v[82:85], v222 offset:2048
	ds_read_b128 v[86:89], v222 offset:6144
	ds_read_b128 v[90:93], v226 offset:2048
	ds_read_b128 v[94:97], v226 offset:6144
	v_mfma_f32_32x32x16_bf16 v[2:17], v[230:233], v[238:241], v[2:17]
	v_mfma_f32_32x32x16_bf16 v[50:65], v[230:233], v[242:245], v[50:65]
	v_mfma_f32_32x32x16_bf16 v[34:49], v[234:237], v[238:241], v[34:49]
	v_mfma_f32_32x32x16_bf16 v[18:33], v[234:237], v[242:245], v[18:33]
	ds_read_b128 v[230:233], v223 offset:2048
	ds_read_b128 v[234:237], v223 offset:6144
	ds_read_b128 v[238:241], v227 offset:2048
	ds_read_b128 v[242:245], v227 offset:6144
	v_mfma_f32_32x32x16_bf16 v[2:17], v[66:69], v[74:77], v[2:17]
	v_mfma_f32_32x32x16_bf16 v[50:65], v[66:69], v[78:81], v[50:65]
	v_mfma_f32_32x32x16_bf16 v[34:49], v[70:73], v[74:77], v[34:49]
	v_mfma_f32_32x32x16_bf16 v[18:33], v[70:73], v[78:81], v[18:33]
	ds_read_b128 v[66:69], v224 offset:2048
	ds_read_b128 v[70:73], v224 offset:6144
	ds_read_b128 v[74:77], v228 offset:2048
	ds_read_b128 v[78:81], v228 offset:6144
	s_waitcnt lgkmcnt(8)
	v_mfma_f32_32x32x16_bf16 v[2:17], v[82:85], v[90:93], v[2:17]
	v_mfma_f32_32x32x16_bf16 v[50:65], v[82:85], v[94:97], v[50:65]
	v_mfma_f32_32x32x16_bf16 v[34:49], v[86:89], v[90:93], v[34:49]
	v_mfma_f32_32x32x16_bf16 v[18:33], v[86:89], v[94:97], v[18:33]
	ds_read_b128 v[82:85], v225 offset:2048
	ds_read_b128 v[86:89], v225 offset:6144
	ds_read_b128 v[90:93], v229 offset:2048
	ds_read_b128 v[94:97], v229 offset:6144
	s_waitcnt lgkmcnt(8)
	v_mfma_f32_32x32x16_bf16 v[2:17], v[230:233], v[238:241], v[2:17]
	v_mfma_f32_32x32x16_bf16 v[50:65], v[230:233], v[242:245], v[50:65]
	v_mfma_f32_32x32x16_bf16 v[34:49], v[234:237], v[238:241], v[34:49]
	v_mfma_f32_32x32x16_bf16 v[18:33], v[234:237], v[242:245], v[18:33]
	s_waitcnt lgkmcnt(0)
	s_barrier
	s_add_u32 m0, s14, 0x500
	s_nop 0
	global_load_lds_dwordx4 v[102:103], off offset:768
	s_add_u32 m0, s14, 0x1500
	s_nop 0
	global_load_lds_dwordx4 v[104:105], off offset:768
	s_add_u32 m0, s14, 0x2500
	s_nop 0
	global_load_lds_dwordx4 v[108:109], off offset:768
	s_add_u32 m0, s14, 0x3500
	s_nop 0
	global_load_lds_dwordx4 v[112:113], off offset:768
	s_add_u32 m0, s14, 0x4500
	s_nop 0
	global_load_lds_dwordx4 v[100:101], off offset:768
	s_add_u32 m0, s14, 0x5500
	s_nop 0
	global_load_lds_dwordx4 v[106:107], off offset:768
	s_add_u32 m0, s14, 0x6500
	s_nop 0
	global_load_lds_dwordx4 v[110:111], off offset:768
	s_add_u32 m0, s14, 0x7500
	s_nop 0
	global_load_lds_dwordx4 v[114:115], off offset:768
	s_waitcnt vmcnt(8)
	s_barrier
	ds_read_b128 v[230:233], v222 offset:34816
	ds_read_b128 v[234:237], v222 offset:38912
	ds_read_b128 v[238:241], v226 offset:34816
	ds_read_b128 v[242:245], v226 offset:38912
	v_mfma_f32_32x32x16_bf16 v[2:17], v[66:69], v[74:77], v[2:17]
	v_mfma_f32_32x32x16_bf16 v[50:65], v[66:69], v[78:81], v[50:65]
	v_mfma_f32_32x32x16_bf16 v[34:49], v[70:73], v[74:77], v[34:49]
	v_mfma_f32_32x32x16_bf16 v[18:33], v[70:73], v[78:81], v[18:33]
	ds_read_b128 v[66:69], v223 offset:34816
	ds_read_b128 v[70:73], v223 offset:38912
	ds_read_b128 v[74:77], v227 offset:34816
	ds_read_b128 v[78:81], v227 offset:38912
	v_mfma_f32_32x32x16_bf16 v[2:17], v[82:85], v[90:93], v[2:17]
	v_mfma_f32_32x32x16_bf16 v[50:65], v[82:85], v[94:97], v[50:65]
	v_mfma_f32_32x32x16_bf16 v[34:49], v[86:89], v[90:93], v[34:49]
	v_mfma_f32_32x32x16_bf16 v[18:33], v[86:89], v[94:97], v[18:33]
	ds_read_b128 v[82:85], v224 offset:34816
	ds_read_b128 v[86:89], v224 offset:38912
	ds_read_b128 v[90:93], v228 offset:34816
	ds_read_b128 v[94:97], v228 offset:38912
	s_waitcnt lgkmcnt(8)
	v_mfma_f32_32x32x16_bf16 v[2:17], v[230:233], v[238:241], v[2:17]
	v_mfma_f32_32x32x16_bf16 v[50:65], v[230:233], v[242:245], v[50:65]
	v_mfma_f32_32x32x16_bf16 v[34:49], v[234:237], v[238:241], v[34:49]
	v_mfma_f32_32x32x16_bf16 v[18:33], v[234:237], v[242:245], v[18:33]
	ds_read_b128 v[230:233], v225 offset:34816
	ds_read_b128 v[234:237], v225 offset:38912
	ds_read_b128 v[238:241], v229 offset:34816
	ds_read_b128 v[242:245], v229 offset:38912
	s_waitcnt lgkmcnt(8)
	v_mfma_f32_32x32x16_bf16 v[2:17], v[66:69], v[74:77], v[2:17]
	v_mfma_f32_32x32x16_bf16 v[50:65], v[66:69], v[78:81], v[50:65]
	v_mfma_f32_32x32x16_bf16 v[34:49], v[70:73], v[74:77], v[34:49]
	v_mfma_f32_32x32x16_bf16 v[18:33], v[70:73], v[78:81], v[18:33]
	s_waitcnt lgkmcnt(0)
	s_barrier
	s_add_u32 m0, s14, 0x8480
	s_nop 0
	global_load_lds_dwordx4 v[102:103], off offset:896
	s_add_u32 m0, s14, 0x9480
	s_nop 0
	global_load_lds_dwordx4 v[104:105], off offset:896
	s_add_u32 m0, s14, 0xa480
	s_nop 0
	global_load_lds_dwordx4 v[108:109], off offset:896
	s_add_u32 m0, s14, 0xb480
	s_nop 0
	global_load_lds_dwordx4 v[112:113], off offset:896
	s_add_u32 m0, s14, 0xc480
	s_nop 0
	global_load_lds_dwordx4 v[100:101], off offset:896
	s_add_u32 m0, s14, 0xd480
	s_nop 0
	global_load_lds_dwordx4 v[106:107], off offset:896
	s_add_u32 m0, s14, 0xe480
	s_nop 0
	global_load_lds_dwordx4 v[110:111], off offset:896
	s_add_u32 m0, s14, 0xf480
	s_nop 0
	global_load_lds_dwordx4 v[114:115], off offset:896
	s_waitcnt vmcnt(8)
	s_barrier
	ds_read_b128 v[66:69], v222 offset:2048
	ds_read_b128 v[70:73], v222 offset:6144
	ds_read_b128 v[74:77], v226 offset:2048
	ds_read_b128 v[78:81], v226 offset:6144
	v_mfma_f32_32x32x16_bf16 v[2:17], v[82:85], v[90:93], v[2:17]
	v_mfma_f32_32x32x16_bf16 v[50:65], v[82:85], v[94:97], v[50:65]
	v_mfma_f32_32x32x16_bf16 v[34:49], v[86:89], v[90:93], v[34:49]
	v_mfma_f32_32x32x16_bf16 v[18:33], v[86:89], v[94:97], v[18:33]
	ds_read_b128 v[82:85], v223 offset:2048
	ds_read_b128 v[86:89], v223 offset:6144
	ds_read_b128 v[90:93], v227 offset:2048
	ds_read_b128 v[94:97], v227 offset:6144
	v_mfma_f32_32x32x16_bf16 v[2:17], v[230:233], v[238:241], v[2:17]
	v_mfma_f32_32x32x16_bf16 v[50:65], v[230:233], v[242:245], v[50:65]
	v_mfma_f32_32x32x16_bf16 v[34:49], v[234:237], v[238:241], v[34:49]
	v_mfma_f32_32x32x16_bf16 v[18:33], v[234:237], v[242:245], v[18:33]
	ds_read_b128 v[230:233], v224 offset:2048
	ds_read_b128 v[234:237], v224 offset:6144
	ds_read_b128 v[238:241], v228 offset:2048
	ds_read_b128 v[242:245], v228 offset:6144
	s_waitcnt lgkmcnt(8)
	v_mfma_f32_32x32x16_bf16 v[2:17], v[66:69], v[74:77], v[2:17]
	v_mfma_f32_32x32x16_bf16 v[50:65], v[66:69], v[78:81], v[50:65]
	v_mfma_f32_32x32x16_bf16 v[34:49], v[70:73], v[74:77], v[34:49]
	v_mfma_f32_32x32x16_bf16 v[18:33], v[70:73], v[78:81], v[18:33]
	ds_read_b128 v[66:69], v225 offset:2048
	ds_read_b128 v[70:73], v225 offset:6144
	ds_read_b128 v[74:77], v229 offset:2048
	ds_read_b128 v[78:81], v229 offset:6144
	s_waitcnt lgkmcnt(8)
	v_mfma_f32_32x32x16_bf16 v[2:17], v[82:85], v[90:93], v[2:17]
	v_mfma_f32_32x32x16_bf16 v[50:65], v[82:85], v[94:97], v[50:65]
	v_mfma_f32_32x32x16_bf16 v[34:49], v[86:89], v[90:93], v[34:49]
	v_mfma_f32_32x32x16_bf16 v[18:33], v[86:89], v[94:97], v[18:33]
	s_waitcnt lgkmcnt(0)
	s_waitcnt vmcnt(0)
	s_barrier
	ds_read_b128 v[82:85], v222 offset:34816
	ds_read_b128 v[86:89], v222 offset:38912
	ds_read_b128 v[90:93], v226 offset:34816
	ds_read_b128 v[94:97], v226 offset:38912
	v_mfma_f32_32x32x16_bf16 v[2:17], v[230:233], v[238:241], v[2:17]
	v_mfma_f32_32x32x16_bf16 v[50:65], v[230:233], v[242:245], v[50:65]
	v_mfma_f32_32x32x16_bf16 v[34:49], v[234:237], v[238:241], v[34:49]
	v_mfma_f32_32x32x16_bf16 v[18:33], v[234:237], v[242:245], v[18:33]
	ds_read_b128 v[230:233], v223 offset:34816
	ds_read_b128 v[234:237], v223 offset:38912
	ds_read_b128 v[238:241], v227 offset:34816
	ds_read_b128 v[242:245], v227 offset:38912
	v_mfma_f32_32x32x16_bf16 v[2:17], v[66:69], v[74:77], v[2:17]
	v_mfma_f32_32x32x16_bf16 v[50:65], v[66:69], v[78:81], v[50:65]
	v_mfma_f32_32x32x16_bf16 v[34:49], v[70:73], v[74:77], v[34:49]
	v_mfma_f32_32x32x16_bf16 v[18:33], v[70:73], v[78:81], v[18:33]
	ds_read_b128 v[66:69], v224 offset:34816
	ds_read_b128 v[70:73], v224 offset:38912
	ds_read_b128 v[74:77], v228 offset:34816
	ds_read_b128 v[78:81], v228 offset:38912
	s_waitcnt lgkmcnt(8)
	v_mfma_f32_32x32x16_bf16 v[2:17], v[82:85], v[90:93], v[2:17]
	v_mfma_f32_32x32x16_bf16 v[50:65], v[82:85], v[94:97], v[50:65]
	v_mfma_f32_32x32x16_bf16 v[34:49], v[86:89], v[90:93], v[34:49]
	v_mfma_f32_32x32x16_bf16 v[18:33], v[86:89], v[94:97], v[18:33]
	ds_read_b128 v[82:85], v225 offset:34816
	ds_read_b128 v[86:89], v225 offset:38912
	ds_read_b128 v[90:93], v229 offset:34816
	ds_read_b128 v[94:97], v229 offset:38912
	s_waitcnt lgkmcnt(8)
	v_mfma_f32_32x32x16_bf16 v[2:17], v[230:233], v[238:241], v[2:17]
	v_mfma_f32_32x32x16_bf16 v[50:65], v[230:233], v[242:245], v[50:65]
	v_mfma_f32_32x32x16_bf16 v[34:49], v[234:237], v[238:241], v[34:49]
	v_mfma_f32_32x32x16_bf16 v[18:33], v[234:237], v[242:245], v[18:33]
	s_waitcnt lgkmcnt(0)
	v_mfma_f32_32x32x16_bf16 v[2:17], v[66:69], v[74:77], v[2:17]
	v_mfma_f32_32x32x16_bf16 v[50:65], v[66:69], v[78:81], v[50:65]
	v_mfma_f32_32x32x16_bf16 v[34:49], v[70:73], v[74:77], v[34:49]
	v_mfma_f32_32x32x16_bf16 v[18:33], v[70:73], v[78:81], v[18:33]
	v_mfma_f32_32x32x16_bf16 v[2:17], v[82:85], v[90:93], v[2:17]
	v_mfma_f32_32x32x16_bf16 v[50:65], v[82:85], v[94:97], v[50:65]
	v_mfma_f32_32x32x16_bf16 v[34:49], v[86:89], v[90:93], v[34:49]
	v_mfma_f32_32x32x16_bf16 v[18:33], v[86:89], v[94:97], v[18:33]
	s_nop 7
	s_nop 7
	s_mov_b64 s[0:1], -1
	s_cmp_eq_u32 s45, 2
	v_and_b32_e32 v92, 0xffff0000, v169
	v_lshlrev_b32_e32 v96, 16, v206
	v_and_b32_e32 v99, 0xffff0000, v206
	v_lshlrev_b32_e32 v100, 16, v207
	v_and_b32_e32 v108, 0xffff0000, v209
	v_lshlrev_b32_e32 v110, 16, v210
	v_and_b32_e32 v111, 0xffff0000, v210
	v_and_b32_e32 v104, 0xffff0000, v207
	v_lshlrev_b32_e32 v105, 16, v208
	v_and_b32_e32 v106, 0xffff0000, v208
	v_lshlrev_b32_e32 v107, 16, v209
	v_lshlrev_b32_e32 v112, 16, v211
	v_and_b32_e32 v114, 0xffff0000, v211
	v_and_b32_e32 v82, 0xffff0000, v171
	v_lshlrev_b32_e32 v83, 16, v170
	v_and_b32_e32 v86, 0xffff0000, v170
	v_lshlrev_b32_e32 v89, 16, v169
	v_cvt_f32_ubyte0_e32 v0, v116
	v_mul_f32_e32 v0, 0x3b808081, v0
	v_lshlrev_b32_e32 v116, 16, v212
	s_waitcnt lgkmcnt(0)
	s_barrier
	s_nop 0
	s_nop 0
	v_cvt_f32_ubyte2_e32 v67, v117
	v_mul_f32_e32 v67, 0x3b808081, v67
	s_nop 8
	v_mul_f32_e32 v4, v67, v4
	v_cvt_f32_ubyte3_e32 v67, v117
	v_mul_f32_e32 v67, 0x3b808081, v67
	v_mul_f32_e32 v5, v67, v5
	v_cvt_f32_ubyte0_e32 v67, v119
	v_mul_f32_e32 v67, 0x3b808081, v67
	v_mul_f32_e32 v6, v67, v6
	v_cvt_f32_ubyte1_e32 v67, v121
	v_mul_f32_e32 v67, 0x3b808081, v67
	v_mul_f32_e32 v7, v67, v7
	v_cvt_f32_ubyte2_e32 v67, v120
	v_mul_f32_e32 v67, 0x3b808081, v67
	v_mul_f32_e32 v8, v67, v8
	v_cvt_f32_ubyte3_e32 v67, v120
	v_mul_f32_e32 v67, 0x3b808081, v67
	v_mul_f32_e32 v9, v67, v9
	v_cvt_f32_ubyte0_e32 v67, v122
	v_mul_f32_e32 v67, 0x3b808081, v67
	v_mul_f32_e32 v10, v67, v10
	v_cvt_f32_ubyte1_e32 v67, v124
	v_mul_f32_e32 v67, 0x3b808081, v67
	v_mul_f32_e32 v11, v67, v11
	v_cvt_f32_ubyte2_e32 v67, v123
	v_mul_f32_e32 v67, 0x3b808081, v67
	v_mul_f32_e32 v12, v67, v12
	v_cvt_f32_ubyte3_e32 v67, v123
	v_mul_f32_e32 v67, 0x3b808081, v67
	v_mul_f32_e32 v13, v67, v13
	v_cvt_f32_ubyte0_e32 v67, v125
	v_mul_f32_e32 v67, 0x3b808081, v67
	v_mul_f32_e32 v14, v67, v14
	v_cvt_f32_ubyte1_e32 v67, v127
	v_mul_f32_e32 v67, 0x3b808081, v67
	v_mul_f32_e32 v15, v67, v15
	v_cvt_f32_ubyte2_e32 v67, v126
	v_mul_f32_e32 v67, 0x3b808081, v67
	v_mul_f32_e32 v67, v67, v16
	v_cvt_f32_ubyte3_e32 v16, v126
	v_mul_f32_e32 v16, 0x3b808081, v16
	v_mul_f32_e32 v68, v16, v17
	v_cvt_f32_ubyte0_e32 v16, v128
	v_mul_f32_e32 v16, 0x3b808081, v16
	v_mul_f32_e32 v50, v16, v50
	v_cvt_f32_ubyte1_e32 v16, v130
	v_mul_f32_e32 v16, 0x3b808081, v16
	v_mul_f32_e32 v51, v16, v51
	v_cvt_f32_ubyte2_e32 v16, v129
	v_mul_f32_e32 v16, 0x3b808081, v16
	v_mul_f32_e32 v52, v16, v52
	v_cvt_f32_ubyte3_e32 v16, v129
	v_mul_f32_e32 v16, 0x3b808081, v16
	v_mul_f32_e32 v53, v16, v53
	v_cvt_f32_ubyte0_e32 v16, v131
	v_mul_f32_e32 v16, 0x3b808081, v16
	v_mul_f32_e32 v54, v16, v54
	v_cvt_f32_ubyte1_e32 v16, v133
	v_mul_f32_e32 v16, 0x3b808081, v16
	v_mul_f32_e32 v55, v16, v55
	v_cvt_f32_ubyte2_e32 v16, v132
	v_mul_f32_e32 v16, 0x3b808081, v16
	v_mul_f32_e32 v56, v16, v56
	v_cvt_f32_ubyte3_e32 v16, v132
	v_mul_f32_e32 v16, 0x3b808081, v16
	v_mul_f32_e32 v57, v16, v57
	v_cvt_f32_ubyte0_e32 v16, v134
	v_mul_f32_e32 v16, 0x3b808081, v16
	v_mul_f32_e32 v58, v16, v58
	v_cvt_f32_ubyte1_e32 v16, v136
	v_mul_f32_e32 v16, 0x3b808081, v16
	v_mul_f32_e32 v59, v16, v59
	v_cvt_f32_ubyte2_e32 v16, v135
	v_mul_f32_e32 v16, 0x3b808081, v16
	v_mul_f32_e32 v60, v16, v60
	v_cvt_f32_ubyte3_e32 v16, v135
	v_mul_f32_e32 v16, 0x3b808081, v16
	v_mul_f32_e32 v61, v16, v61
	v_cvt_f32_ubyte0_e32 v16, v137
	v_mul_f32_e32 v16, 0x3b808081, v16
	s_nop 0
	v_mul_f32_e32 v62, v16, v62
	v_cvt_f32_ubyte1_e32 v16, v139
	v_mul_f32_e32 v16, 0x3b808081, v16
	v_mul_f32_e32 v63, v16, v63
	v_cvt_f32_ubyte2_e32 v16, v138
	v_mul_f32_e32 v16, 0x3b808081, v16
	v_mul_f32_e32 v64, v16, v64
	v_cvt_f32_ubyte3_e32 v16, v138
	v_mul_f32_e32 v16, 0x3b808081, v16
	v_mul_f32_e32 v65, v16, v65
	v_cvt_f32_ubyte0_e32 v16, v140
	v_mul_f32_e32 v16, 0x3b808081, v16
	v_mul_f32_e32 v34, v16, v34
	v_cvt_f32_ubyte1_e32 v16, v142
	v_mul_f32_e32 v16, 0x3b808081, v16
	v_mul_f32_e32 v35, v16, v35
	v_cvt_f32_ubyte2_e32 v16, v141
	v_mul_f32_e32 v16, 0x3b808081, v16
	v_mul_f32_e32 v36, v16, v36
	v_cvt_f32_ubyte3_e32 v16, v141
	v_mul_f32_e32 v16, 0x3b808081, v16
	v_mul_f32_e32 v37, v16, v37
	v_cvt_f32_ubyte0_e32 v16, v143
	v_mul_f32_e32 v16, 0x3b808081, v16
	v_mul_f32_e32 v38, v16, v38
	v_cvt_f32_ubyte1_e32 v16, v145
	v_mul_f32_e32 v16, 0x3b808081, v16
	v_mul_f32_e32 v39, v16, v39
	v_cvt_f32_ubyte2_e32 v16, v144
	v_mul_f32_e32 v16, 0x3b808081, v16
	v_mul_f32_e32 v40, v16, v40
	v_cvt_f32_ubyte3_e32 v16, v144
	v_mul_f32_e32 v16, 0x3b808081, v16
	v_mul_f32_e32 v69, v16, v41
	v_cvt_f32_ubyte0_e32 v16, v146
	v_mul_f32_e32 v16, 0x3b808081, v16
	s_nop 0
	v_mul_f32_e32 v70, v16, v42
	v_cvt_f32_ubyte1_e32 v16, v148
	v_mul_f32_e32 v16, 0x3b808081, v16
	v_mul_f32_e32 v76, v16, v43
	v_cvt_f32_ubyte2_e32 v16, v147
	v_mul_f32_e32 v16, 0x3b808081, v16
	v_mul_f32_e32 v78, v16, v44
	v_cvt_f32_ubyte3_e32 v16, v147
	v_mul_f32_e32 v16, 0x3b808081, v16
	v_mul_f32_e32 v81, v16, v45
	v_cvt_f32_ubyte0_e32 v16, v149
	v_mul_f32_e32 v16, 0x3b808081, v16
	v_mul_f32_e32 v93, v16, v46
	v_cvt_f32_ubyte1_e32 v16, v151
	v_mul_f32_e32 v16, 0x3b808081, v16
	v_mul_f32_e32 v101, v16, v47
	v_cvt_f32_ubyte2_e32 v16, v150
	v_mul_f32_e32 v16, 0x3b808081, v16
	v_mul_f32_e32 v109, v16, v48
	v_cvt_f32_ubyte3_e32 v16, v150
	v_mul_f32_e32 v16, 0x3b808081, v16
	v_mul_f32_e32 v113, v16, v49
	v_cvt_f32_ubyte0_e32 v16, v152
	v_mul_f32_e32 v16, 0x3b808081, v16
	v_mul_f32_e32 v115, v16, v18
	v_cvt_f32_ubyte1_e32 v16, v154
	v_mul_f32_e32 v16, 0x3b808081, v16
	v_mul_f32_e32 v117, v16, v19
	v_cvt_f32_ubyte2_e32 v16, v153
	v_mul_f32_e32 v16, 0x3b808081, v16
	v_cvt_f32_ubyte1_e32 v66, v118
	v_mul_f32_e32 v118, v16, v20
	v_cvt_f32_ubyte3_e32 v16, v153
	v_mul_f32_e32 v16, 0x3b808081, v16
	v_mul_f32_e32 v119, v16, v21
	v_cvt_f32_ubyte0_e32 v16, v155
	v_mul_f32_e32 v16, 0x3b808081, v16
	v_mul_f32_e32 v120, v16, v22
	v_cvt_f32_ubyte1_e32 v16, v157
	v_mul_f32_e32 v16, 0x3b808081, v16
	v_mul_f32_e32 v122, v16, v23
	v_cvt_f32_ubyte2_e32 v16, v156
	v_mul_f32_e32 v16, 0x3b808081, v16
	v_mul_f32_e32 v123, v16, v24
	v_cvt_f32_ubyte3_e32 v16, v156
	v_mul_f32_e32 v16, 0x3b808081, v16
	v_mul_f32_e32 v124, v16, v25
	v_cvt_f32_ubyte0_e32 v16, v158
	v_mul_f32_e32 v16, 0x3b808081, v16
	v_mul_f32_e32 v125, v16, v26
	v_cvt_f32_ubyte1_e32 v16, v160
	v_mul_f32_e32 v16, 0x3b808081, v16
	v_mul_f32_e32 v127, v16, v27
	v_cvt_f32_ubyte2_e32 v16, v159
	v_mul_f32_e32 v16, 0x3b808081, v16
	v_mul_f32_e32 v128, v16, v28
	v_cvt_f32_ubyte3_e32 v16, v159
	v_mul_f32_e32 v16, 0x3b808081, v16
	v_mul_f32_e32 v129, v16, v29
	v_cvt_f32_ubyte0_e32 v16, v161
	v_mul_f32_e32 v16, 0x3b808081, v16
	v_mul_f32_e32 v130, v16, v30
	v_cvt_f32_ubyte1_e32 v16, v163
	v_mul_f32_e32 v16, 0x3b808081, v16
	v_mul_f32_e32 v132, v16, v31
	v_cvt_f32_ubyte2_e32 v16, v162
	v_mul_f32_e32 v16, 0x3b808081, v16
	v_mul_f32_e32 v133, v16, v32
	v_cvt_f32_ubyte3_e32 v16, v162
	v_mul_f32_e32 v16, 0x3b808081, v16
	v_mul_f32_e32 v66, 0x3b808081, v66
	v_mul_f32_e32 v134, v16, v33
	v_lshlrev_b32_e32 v16, 16, v205
	v_and_b32_e32 v17, 0xffff0000, v205
	v_lshlrev_b32_e32 v18, 16, v204
	v_and_b32_e32 v19, 0xffff0000, v204
	v_lshlrev_b32_e32 v20, 16, v203
	v_and_b32_e32 v21, 0xffff0000, v203
	v_lshlrev_b32_e32 v22, 16, v202
	v_and_b32_e32 v23, 0xffff0000, v202
	v_lshlrev_b32_e32 v24, 16, v201
	v_and_b32_e32 v25, 0xffff0000, v201
	v_lshlrev_b32_e32 v28, 16, v200
	v_and_b32_e32 v31, 0xffff0000, v200
	v_lshlrev_b32_e32 v41, 16, v199
	v_and_b32_e32 v44, 0xffff0000, v199
	v_lshlrev_b32_e32 v45, 16, v177
	v_and_b32_e32 v46, 0xffff0000, v177
	v_lshlrev_b32_e32 v47, 16, v176
	v_and_b32_e32 v48, 0xffff0000, v176
	v_lshlrev_b32_e32 v49, 16, v175
	v_and_b32_e32 v71, 0xffff0000, v175
	v_lshlrev_b32_e32 v72, 16, v174
	v_and_b32_e32 v73, 0xffff0000, v174
	v_lshlrev_b32_e32 v74, 16, v173
	v_and_b32_e32 v75, 0xffff0000, v173
	v_lshlrev_b32_e32 v77, 16, v172
	v_and_b32_e32 v79, 0xffff0000, v172
	v_lshlrev_b32_e32 v80, 16, v171
	v_and_b32_e32 v121, 0xffff0000, v212
	v_lshlrev_b32_e32 v126, 16, v213
	v_and_b32_e32 v131, 0xffff0000, v213
	v_lshlrev_b32_e32 v135, 16, v214
	v_and_b32_e32 v136, 0xffff0000, v214
	v_lshlrev_b32_e32 v137, 16, v215
	v_and_b32_e32 v138, 0xffff0000, v215
	v_lshlrev_b32_e32 v139, 16, v216
	v_and_b32_e32 v140, 0xffff0000, v216
	v_lshlrev_b32_e32 v141, 16, v217
	v_and_b32_e32 v142, 0xffff0000, v217
	v_lshlrev_b32_e32 v143, 16, v218
	v_and_b32_e32 v144, 0xffff0000, v218
	v_lshlrev_b32_e32 v145, 16, v219
	v_and_b32_e32 v146, 0xffff0000, v219
	v_lshlrev_b32_e32 v147, 16, v220
	v_and_b32_e32 v148, 0xffff0000, v220
	v_lshlrev_b32_e32 v149, 16, v221
	v_and_b32_e32 v150, 0xffff0000, v221
	v_fmac_f32_e32 v16, v0, v2
	v_fmac_f32_e32 v17, v66, v3
	v_add_f32_e32 v42, v4, v18
	v_add_f32_e32 v43, v5, v19
	v_add_f32_e32 v32, v6, v20
	v_add_f32_e32 v33, v7, v21
	v_add_f32_e32 v29, v8, v22
	v_add_f32_e32 v30, v9, v23
	v_add_f32_e32 v26, v10, v24
	v_add_f32_e32 v27, v11, v25
	v_add_f32_e32 v23, v12, v28
	v_add_f32_e32 v24, v13, v31
	v_add_f32_e32 v21, v14, v41
	v_add_f32_e32 v20, v15, v44
	v_add_f32_e32 v19, v67, v45
	v_add_f32_e32 v18, v68, v46
	v_add_f32_e32 v102, v50, v47
	v_add_f32_e32 v103, v51, v48
	v_add_f32_e32 v97, v52, v49
	v_add_f32_e32 v98, v53, v71
	v_add_f32_e32 v94, v54, v72
	v_add_f32_e32 v95, v55, v73
	v_add_f32_e32 v90, v56, v74
	v_add_f32_e32 v91, v57, v75
	v_add_f32_e32 v87, v58, v77
	v_add_f32_e32 v88, v59, v79
	v_add_f32_e32 v84, v60, v80
	v_add_f32_e32 v85, v61, v82
	v_add_f32_e32 v82, v62, v83
	v_add_f32_e32 v80, v63, v86
	v_add_f32_e32 v79, v64, v89
	v_add_f32_e32 v77, v65, v92
	v_add_f32_e32 v75, v34, v96
	v_add_f32_e32 v73, v35, v99
	v_add_f32_e32 v74, v36, v100
	v_add_f32_e32 v72, v37, v104
	v_add_f32_e32 v71, v38, v105
	v_add_f32_e32 v48, v39, v106
	v_add_f32_e32 v49, v40, v107
	v_add_f32_e32 v47, v69, v108
	v_add_f32_e32 v46, v70, v110
	v_add_f32_e32 v44, v76, v111
	v_add_f32_e32 v45, v78, v112
	v_add_f32_e32 v41, v81, v114
	v_add_f32_e32 v31, v93, v116
	v_add_f32_e32 v28, v101, v121
	v_add_f32_e32 v25, v109, v126
	v_add_f32_e32 v22, v113, v131
	v_add_f32_e32 v114, v115, v135
	v_add_f32_e32 v111, v117, v136
	v_add_f32_e32 v112, v118, v137
	v_add_f32_e32 v110, v119, v138
	v_add_f32_e32 v108, v120, v139
	v_add_f32_e32 v106, v122, v140
	v_add_f32_e32 v107, v123, v141
	v_add_f32_e32 v105, v124, v142
	v_add_f32_e32 v104, v125, v143
	v_add_f32_e32 v99, v127, v144
	v_add_f32_e32 v100, v128, v145
	v_add_f32_e32 v96, v129, v146
	v_add_f32_e32 v92, v130, v147
	v_add_f32_e32 v89, v132, v148
	v_add_f32_e32 v86, v133, v149
	v_add_f32_e32 v83, v134, v150
	s_cbranch_scc1 .LBB0_857
	v_mul_f32_e32 v0, v0, v2
	v_mul_f32_e32 v2, v66, v3
	v_cndmask_b32_e32 v0, v16, v0, vcc
	v_cndmask_b32_e32 v2, v17, v2, vcc
	v_cvt_pk_bf16_f32 v116, v0, v2
	v_cndmask_b32_e32 v0, v42, v4, vcc
	v_cndmask_b32_e32 v2, v43, v5, vcc
	v_cvt_pk_bf16_f32 v121, v0, v2
	v_cndmask_b32_e32 v0, v32, v6, vcc
	v_cndmask_b32_e32 v2, v33, v7, vcc
	v_cvt_pk_bf16_f32 v126, v0, v2
	v_cndmask_b32_e32 v0, v29, v8, vcc
	v_cndmask_b32_e32 v2, v30, v9, vcc
	v_cvt_pk_bf16_f32 v131, v0, v2
	v_cndmask_b32_e32 v0, v26, v10, vcc
	v_cndmask_b32_e32 v2, v27, v11, vcc
	v_cvt_pk_bf16_f32 v135, v0, v2
	v_cndmask_b32_e32 v0, v23, v12, vcc
	v_cndmask_b32_e32 v2, v24, v13, vcc
	v_cvt_pk_bf16_f32 v136, v0, v2
	v_cndmask_b32_e32 v0, v21, v14, vcc
	v_cndmask_b32_e32 v2, v20, v15, vcc
	v_cvt_pk_bf16_f32 v137, v0, v2
	v_cndmask_b32_e32 v0, v19, v67, vcc
	v_cndmask_b32_e32 v2, v18, v68, vcc
	v_cvt_pk_bf16_f32 v138, v0, v2
	v_cndmask_b32_e32 v0, v102, v50, vcc
	v_cndmask_b32_e32 v2, v103, v51, vcc
	v_cvt_pk_bf16_f32 v155, v0, v2
	v_cndmask_b32_e32 v0, v97, v52, vcc
	v_cndmask_b32_e32 v2, v98, v53, vcc
	v_cvt_pk_bf16_f32 v156, v0, v2
	v_cndmask_b32_e32 v0, v94, v54, vcc
	v_cndmask_b32_e32 v2, v95, v55, vcc
	v_cvt_pk_bf16_f32 v157, v0, v2
	v_cndmask_b32_e32 v0, v90, v56, vcc
	v_cndmask_b32_e32 v2, v91, v57, vcc
	v_cvt_pk_bf16_f32 v158, v0, v2
	v_cndmask_b32_e32 v0, v87, v58, vcc
	v_cndmask_b32_e32 v2, v88, v59, vcc
	v_cvt_pk_bf16_f32 v159, v0, v2
	v_cndmask_b32_e32 v0, v84, v60, vcc
	v_cndmask_b32_e32 v2, v85, v61, vcc
	v_cvt_pk_bf16_f32 v160, v0, v2
	v_cndmask_b32_e32 v0, v82, v62, vcc
	v_cndmask_b32_e32 v2, v80, v63, vcc
	v_cvt_pk_bf16_f32 v161, v0, v2
	v_cndmask_b32_e32 v0, v79, v64, vcc
	v_cndmask_b32_e32 v2, v77, v65, vcc
	v_cvt_pk_bf16_f32 v162, v0, v2
	v_cndmask_b32_e32 v0, v75, v34, vcc
	v_cndmask_b32_e32 v2, v73, v35, vcc
	v_cvt_pk_bf16_f32 v154, v0, v2
	v_cndmask_b32_e32 v0, v74, v36, vcc
	v_cndmask_b32_e32 v2, v72, v37, vcc
	v_cvt_pk_bf16_f32 v153, v0, v2
	v_cndmask_b32_e32 v0, v71, v38, vcc
	v_cndmask_b32_e32 v2, v48, v39, vcc
	v_cvt_pk_bf16_f32 v152, v0, v2
	v_cndmask_b32_e32 v0, v49, v40, vcc
	v_cndmask_b32_e32 v2, v47, v69, vcc
	v_cvt_pk_bf16_f32 v151, v0, v2
	v_cndmask_b32_e32 v0, v46, v70, vcc
	v_cndmask_b32_e32 v2, v44, v76, vcc
	v_cvt_pk_bf16_f32 v150, v0, v2
	v_cndmask_b32_e32 v0, v45, v78, vcc
	v_cndmask_b32_e32 v2, v41, v81, vcc
	v_cvt_pk_bf16_f32 v149, v0, v2
	v_cndmask_b32_e32 v0, v31, v93, vcc
	v_cndmask_b32_e32 v2, v28, v101, vcc
	v_cvt_pk_bf16_f32 v148, v0, v2
	v_cndmask_b32_e32 v0, v25, v109, vcc
	v_cndmask_b32_e32 v2, v22, v113, vcc
	v_cvt_pk_bf16_f32 v147, v0, v2
	v_cndmask_b32_e32 v0, v114, v115, vcc
	v_cndmask_b32_e32 v2, v111, v117, vcc
	v_cvt_pk_bf16_f32 v146, v0, v2
	v_cndmask_b32_e32 v0, v112, v118, vcc
	v_cndmask_b32_e32 v2, v110, v119, vcc
	v_cvt_pk_bf16_f32 v145, v0, v2
	v_cndmask_b32_e32 v0, v108, v120, vcc
	v_cndmask_b32_e32 v2, v106, v122, vcc
	v_cvt_pk_bf16_f32 v144, v0, v2
	v_cndmask_b32_e32 v0, v107, v123, vcc
	v_cndmask_b32_e32 v2, v105, v124, vcc
	v_cvt_pk_bf16_f32 v143, v0, v2
	v_cndmask_b32_e32 v0, v104, v125, vcc
	v_cndmask_b32_e32 v2, v99, v127, vcc
	v_cvt_pk_bf16_f32 v142, v0, v2
	v_cndmask_b32_e32 v0, v100, v128, vcc
	v_cndmask_b32_e32 v2, v96, v129, vcc
	v_cvt_pk_bf16_f32 v141, v0, v2
	v_cndmask_b32_e32 v0, v92, v130, vcc
	v_cndmask_b32_e32 v2, v89, v132, vcc
	v_cvt_pk_bf16_f32 v140, v0, v2
	v_cndmask_b32_e32 v0, v86, v133, vcc
	v_cndmask_b32_e32 v2, v83, v134, vcc
	v_cvt_pk_bf16_f32 v139, v0, v2
	s_mov_b64 s[0:1], 0
